# DN phases: last K iteration peeled, first two row-blocks of the residual loaded half an iteration early (on v5)
# baseline (speedup 1.0000x reference)
.LBB0_357:
	ds_read_b128 v[134:137], v190
	ds_read_b128 v[138:141], v190 offset:1024
	ds_read_b128 v[142:145], v190 offset:2048
	ds_read_b128 v[146:149], v190 offset:3072
	s_mov_b32 m0, s54
	v_lshl_add_u64 v[150:151], v[128:129], 0, s[34:35]
	ds_read_b128 v[166:169], v191
	ds_read_b128 v[170:173], v191 offset:1024
	ds_read_b128 v[174:177], v191 offset:2048
	ds_read_b128 v[178:181], v191 offset:3072
	ds_read_b128 v[194:197], v191 offset:4096
	ds_read_b128 v[198:201], v191 offset:5120
	ds_read_b128 v[202:205], v191 offset:6144
	ds_read_b128 v[206:209], v191 offset:7168
	global_load_lds_dwordx4 v[150:151], off
	s_mov_b32 m0, s55
	v_lshl_add_u64 v[150:151], v[130:131], 0, s[34:35]
	global_load_lds_dwordx4 v[150:151], off
	s_waitcnt lgkmcnt(8)
	s_barrier
	s_waitcnt lgkmcnt(0)
	s_setprio 1
	v_mfma_f32_16x16x32_bf16 v[116:119], v[134:137], v[166:169], v[116:119]
	s_add_i32 s36, s34, 0xfff50080
	v_mfma_f32_16x16x32_bf16 v[112:115], v[142:145], v[166:169], v[112:115]
	s_cmp_eq_u32 s67, 40
	v_mfma_f32_16x16x32_bf16 v[108:111], v[134:137], v[174:177], v[108:111]
	s_cselect_b32 s69, s27, s29
	v_mfma_f32_16x16x32_bf16 v[104:107], v[142:145], v[174:177], v[104:107]
	s_cselect_b32 s68, s26, s28
	v_mfma_f32_16x16x32_bf16 v[92:95], v[134:137], v[194:197], v[92:95]
	s_cselect_b32 s37, s9, s31
	v_mfma_f32_16x16x32_bf16 v[88:91], v[142:145], v[194:197], v[88:91]
	s_cselect_b32 s70, s8, s30
	v_mfma_f32_16x16x32_bf16 v[76:79], v[134:137], v[202:205], v[76:79]
	v_mfma_f32_16x16x32_bf16 v[72:75], v[142:145], v[202:205], v[72:75]
	v_mfma_f32_16x16x32_bf16 v[116:119], v[138:141], v[170:173], v[116:119]
	v_mfma_f32_16x16x32_bf16 v[112:115], v[146:149], v[170:173], v[112:115]
	v_mfma_f32_16x16x32_bf16 v[108:111], v[138:141], v[178:181], v[108:111]
	v_mfma_f32_16x16x32_bf16 v[104:107], v[146:149], v[178:181], v[104:107]
	v_mfma_f32_16x16x32_bf16 v[92:95], v[138:141], v[198:201], v[92:95]
	v_mfma_f32_16x16x32_bf16 v[88:91], v[146:149], v[198:201], v[88:91]
	v_mfma_f32_16x16x32_bf16 v[76:79], v[138:141], v[206:209], v[76:79]
	v_mfma_f32_16x16x32_bf16 v[72:75], v[146:149], v[206:209], v[72:75]
	s_setprio 0
	s_barrier
	s_cselect_b32 s71, 0, s36
	s_add_u32 s36, s70, s71
	s_addc_u32 s37, s37, 0
	s_mov_b32 m0, s56
	v_lshl_add_u64 v[150:151], s[36:37], 0, v[156:157]
	ds_read_b128 v[210:213], v192
	ds_read_b128 v[214:217], v192 offset:1024
	ds_read_b128 v[222:225], v192 offset:2048
	ds_read_b128 v[226:229], v192 offset:3072
	global_load_lds_dwordx4 v[150:151], off
	s_mov_b32 m0, s57
	v_lshl_add_u64 v[182:183], s[36:37], 0, v[160:161]
	global_load_lds_dwordx4 v[182:183], off
	s_barrier
	s_waitcnt lgkmcnt(0)
	s_setprio 1
	v_mfma_f32_16x16x32_bf16 v[124:127], v[210:213], v[166:169], v[124:127]
	v_mfma_f32_16x16x32_bf16 v[120:123], v[222:225], v[166:169], v[120:123]
	v_mfma_f32_16x16x32_bf16 v[100:103], v[210:213], v[174:177], v[100:103]
	v_mfma_f32_16x16x32_bf16 v[96:99], v[222:225], v[174:177], v[96:99]
	v_mfma_f32_16x16x32_bf16 v[84:87], v[210:213], v[194:197], v[84:87]
	v_mfma_f32_16x16x32_bf16 v[80:83], v[222:225], v[194:197], v[80:83]
	v_mfma_f32_16x16x32_bf16 v[68:71], v[210:213], v[202:205], v[68:71]
	v_mfma_f32_16x16x32_bf16 v[64:67], v[222:225], v[202:205], v[64:67]
	v_mfma_f32_16x16x32_bf16 v[124:127], v[214:217], v[170:173], v[124:127]
	v_mfma_f32_16x16x32_bf16 v[120:123], v[226:229], v[170:173], v[120:123]
	v_mfma_f32_16x16x32_bf16 v[100:103], v[214:217], v[178:181], v[100:103]
	v_mfma_f32_16x16x32_bf16 v[96:99], v[226:229], v[178:181], v[96:99]
	v_mfma_f32_16x16x32_bf16 v[84:87], v[214:217], v[198:201], v[84:87]
	v_mfma_f32_16x16x32_bf16 v[80:83], v[226:229], v[198:201], v[80:83]
	v_mfma_f32_16x16x32_bf16 v[68:71], v[214:217], v[206:209], v[68:71]
	v_mfma_f32_16x16x32_bf16 v[64:67], v[226:229], v[206:209], v[64:67]
	s_setprio 0
	s_add_u32 s68, s68, s71
	s_addc_u32 s69, s69, 0
	s_mov_b32 m0, s46
	v_lshl_add_u64 v[218:219], s[68:69], 0, v[154:155]
	s_barrier
	ds_read_b128 v[166:169], v191 offset:16384
	ds_read_b128 v[170:173], v191 offset:17408
	ds_read_b128 v[174:177], v191 offset:18432
	ds_read_b128 v[178:181], v191 offset:19456
	ds_read_b128 v[194:197], v191 offset:20480
	ds_read_b128 v[198:201], v191 offset:21504
	ds_read_b128 v[202:205], v191 offset:22528
	ds_read_b128 v[206:209], v191 offset:23552
	global_load_lds_dwordx4 v[218:219], off
	s_mov_b32 m0, s47
	v_lshl_add_u64 v[230:231], s[68:69], 0, v[158:159]
	global_load_lds_dwordx4 v[230:231], off
	s_barrier
	s_waitcnt lgkmcnt(0)
	s_setprio 1
	v_mfma_f32_16x16x32_bf16 v[52:55], v[134:137], v[166:169], v[52:55]
	v_mfma_f32_16x16x32_bf16 v[48:51], v[142:145], v[166:169], v[48:51]
	v_mfma_f32_16x16x32_bf16 v[44:47], v[134:137], v[174:177], v[44:47]
	v_mfma_f32_16x16x32_bf16 v[36:39], v[142:145], v[174:177], v[36:39]
	v_mfma_f32_16x16x32_bf16 v[28:31], v[134:137], v[194:197], v[28:31]
	v_mfma_f32_16x16x32_bf16 v[20:23], v[142:145], v[194:197], v[20:23]
	v_mfma_f32_16x16x32_bf16 v[12:15], v[134:137], v[202:205], v[12:15]
	v_mfma_f32_16x16x32_bf16 v[4:7], v[142:145], v[202:205], v[4:7]
	v_mfma_f32_16x16x32_bf16 v[52:55], v[138:141], v[170:173], v[52:55]
	v_mfma_f32_16x16x32_bf16 v[48:51], v[146:149], v[170:173], v[48:51]
	v_mfma_f32_16x16x32_bf16 v[44:47], v[138:141], v[178:181], v[44:47]
	v_mfma_f32_16x16x32_bf16 v[36:39], v[146:149], v[178:181], v[36:39]
	v_mfma_f32_16x16x32_bf16 v[28:31], v[138:141], v[198:201], v[28:31]
	v_mfma_f32_16x16x32_bf16 v[20:23], v[146:149], v[198:201], v[20:23]
	v_mfma_f32_16x16x32_bf16 v[12:15], v[138:141], v[206:209], v[12:15]
	v_mfma_f32_16x16x32_bf16 v[4:7], v[146:149], v[206:209], v[4:7]
	s_setprio 0
	s_barrier
	s_add_u32 s70, s36, 0xb0000
	s_addc_u32 s71, s37, 0
	s_mov_b32 m0, s0
	v_lshl_add_u64 v[134:135], s[70:71], 0, v[156:157]
	global_load_lds_dwordx4 v[134:135], off
	s_mov_b32 m0, s62
	v_lshl_add_u64 v[134:135], s[70:71], 0, v[160:161]
	global_load_lds_dwordx4 v[134:135], off
	s_waitcnt vmcnt(6)
	s_barrier
	s_setprio 1
	v_mfma_f32_16x16x32_bf16 v[60:63], v[210:213], v[166:169], v[60:63]
	v_mfma_f32_16x16x32_bf16 v[56:59], v[222:225], v[166:169], v[56:59]
	v_mfma_f32_16x16x32_bf16 v[40:43], v[210:213], v[174:177], v[40:43]
	v_mfma_f32_16x16x32_bf16 v[32:35], v[222:225], v[174:177], v[32:35]
	v_mfma_f32_16x16x32_bf16 v[24:27], v[210:213], v[194:197], v[24:27]
	v_mfma_f32_16x16x32_bf16 v[16:19], v[222:225], v[194:197], v[16:19]
	v_mfma_f32_16x16x32_bf16 v[8:11], v[210:213], v[202:205], v[8:11]
	v_mfma_f32_16x16x32_bf16 v[0:3], v[222:225], v[202:205], v[0:3]
	v_mfma_f32_16x16x32_bf16 v[60:63], v[214:217], v[170:173], v[60:63]
	v_mfma_f32_16x16x32_bf16 v[56:59], v[226:229], v[170:173], v[56:59]
	v_mfma_f32_16x16x32_bf16 v[40:43], v[214:217], v[178:181], v[40:43]
	v_mfma_f32_16x16x32_bf16 v[32:35], v[226:229], v[178:181], v[32:35]
	v_mfma_f32_16x16x32_bf16 v[24:27], v[214:217], v[198:201], v[24:27]
	v_mfma_f32_16x16x32_bf16 v[16:19], v[226:229], v[198:201], v[16:19]
	v_mfma_f32_16x16x32_bf16 v[8:11], v[214:217], v[206:209], v[8:11]
	v_mfma_f32_16x16x32_bf16 v[0:3], v[226:229], v[206:209], v[0:3]
	s_setprio 0
	s_barrier
	ds_read_b128 v[134:137], v132
	ds_read_b128 v[138:141], v132 offset:1024
	ds_read_b128 v[142:145], v132 offset:2048
	ds_read_b128 v[146:149], v132 offset:3072
	s_add_u32 s68, s68, 0xb0000
	s_addc_u32 s69, s69, 0
	s_mov_b32 m0, s48
	v_lshl_add_u64 v[210:211], s[68:69], 0, v[154:155]
	ds_read_b128 v[166:169], v191 offset:32768
	ds_read_b128 v[170:173], v191 offset:33792
	ds_read_b128 v[174:177], v191 offset:34816
	ds_read_b128 v[178:181], v191 offset:35840
	ds_read_b128 v[194:197], v191 offset:36864
	ds_read_b128 v[198:201], v191 offset:37888
	ds_read_b128 v[202:205], v191 offset:38912
	ds_read_b128 v[206:209], v191 offset:39936
	global_load_lds_dwordx4 v[210:211], off
	s_mov_b32 m0, s49
	v_lshl_add_u64 v[210:211], s[68:69], 0, v[158:159]
	global_load_lds_dwordx4 v[210:211], off
	s_waitcnt lgkmcnt(8)
	s_barrier
	s_waitcnt lgkmcnt(0)
	s_setprio 1
	v_mfma_f32_16x16x32_bf16 v[116:119], v[134:137], v[166:169], v[116:119]
	v_mfma_f32_16x16x32_bf16 v[112:115], v[142:145], v[166:169], v[112:115]
	v_mfma_f32_16x16x32_bf16 v[108:111], v[134:137], v[174:177], v[108:111]
	v_mfma_f32_16x16x32_bf16 v[104:107], v[142:145], v[174:177], v[104:107]
	v_mfma_f32_16x16x32_bf16 v[92:95], v[134:137], v[194:197], v[92:95]
	v_mfma_f32_16x16x32_bf16 v[88:91], v[142:145], v[194:197], v[88:91]
	v_mfma_f32_16x16x32_bf16 v[76:79], v[134:137], v[202:205], v[76:79]
	v_mfma_f32_16x16x32_bf16 v[72:75], v[142:145], v[202:205], v[72:75]
	v_mfma_f32_16x16x32_bf16 v[116:119], v[138:141], v[170:173], v[116:119]
	v_mfma_f32_16x16x32_bf16 v[112:115], v[146:149], v[170:173], v[112:115]
	v_mfma_f32_16x16x32_bf16 v[108:111], v[138:141], v[178:181], v[108:111]
	v_mfma_f32_16x16x32_bf16 v[104:107], v[146:149], v[178:181], v[104:107]
	v_mfma_f32_16x16x32_bf16 v[92:95], v[138:141], v[198:201], v[92:95]
	v_mfma_f32_16x16x32_bf16 v[88:91], v[146:149], v[198:201], v[88:91]
	v_mfma_f32_16x16x32_bf16 v[76:79], v[138:141], v[206:209], v[76:79]
	v_mfma_f32_16x16x32_bf16 v[72:75], v[146:149], v[206:209], v[72:75]
	s_setprio 0
	s_barrier
	s_mov_b32 m0, s63
	v_lshl_add_u64 v[150:151], v[150:151], 0, s[10:11]
	ds_read_b128 v[210:213], v133
	ds_read_b128 v[214:217], v133 offset:1024
	ds_read_b128 v[222:225], v133 offset:2048
	ds_read_b128 v[226:229], v133 offset:3072
	global_load_lds_dwordx4 v[150:151], off
	s_mov_b32 m0, s64
	v_lshl_add_u64 v[150:151], v[182:183], 0, s[10:11]
	global_load_lds_dwordx4 v[150:151], off
	s_barrier
	s_waitcnt lgkmcnt(0)
	s_setprio 1
	v_mfma_f32_16x16x32_bf16 v[124:127], v[210:213], v[166:169], v[124:127]
	v_mfma_f32_16x16x32_bf16 v[120:123], v[222:225], v[166:169], v[120:123]
	v_mfma_f32_16x16x32_bf16 v[100:103], v[210:213], v[174:177], v[100:103]
	v_mfma_f32_16x16x32_bf16 v[96:99], v[222:225], v[174:177], v[96:99]
	v_mfma_f32_16x16x32_bf16 v[84:87], v[210:213], v[194:197], v[84:87]
	v_mfma_f32_16x16x32_bf16 v[80:83], v[222:225], v[194:197], v[80:83]
	v_mfma_f32_16x16x32_bf16 v[68:71], v[210:213], v[202:205], v[68:71]
	v_mfma_f32_16x16x32_bf16 v[64:67], v[222:225], v[202:205], v[64:67]
	v_mfma_f32_16x16x32_bf16 v[124:127], v[214:217], v[170:173], v[124:127]
	v_mfma_f32_16x16x32_bf16 v[120:123], v[226:229], v[170:173], v[120:123]
	v_mfma_f32_16x16x32_bf16 v[100:103], v[214:217], v[178:181], v[100:103]
	v_mfma_f32_16x16x32_bf16 v[96:99], v[226:229], v[178:181], v[96:99]
	v_mfma_f32_16x16x32_bf16 v[84:87], v[214:217], v[198:201], v[84:87]
	v_mfma_f32_16x16x32_bf16 v[80:83], v[226:229], v[198:201], v[80:83]
	v_mfma_f32_16x16x32_bf16 v[68:71], v[214:217], v[206:209], v[68:71]
	v_mfma_f32_16x16x32_bf16 v[64:67], v[226:229], v[206:209], v[64:67]
	s_setprio 0
	s_mov_b32 m0, s51
	v_lshl_add_u64 v[150:151], v[218:219], 0, s[10:11]
	s_barrier
	ds_read_b128 v[166:169], v191 offset:49152
	ds_read_b128 v[170:173], v191 offset:50176
	ds_read_b128 v[174:177], v191 offset:51200
	ds_read_b128 v[178:181], v191 offset:52224
	ds_read_b128 v[194:197], v191 offset:53248
	ds_read_b128 v[198:201], v191 offset:54272
	ds_read_b128 v[202:205], v191 offset:55296
	ds_read_b128 v[206:209], v191 offset:56320
	global_load_lds_dwordx4 v[150:151], off
	s_mov_b32 m0, s52
	v_lshl_add_u64 v[150:151], v[230:231], 0, s[10:11]
	global_load_lds_dwordx4 v[150:151], off
	s_barrier
;     ...
;         G_PAIR(0, 1);
; #pragma unroll 1
;         for (int t = 2; t < nt; t += 2) G_PAIR(t, 0);
	s_waitcnt lgkmcnt(0)
	s_setprio 1
	v_mfma_f32_16x16x32_bf16 v[52:55], v[134:137], v[166:169], v[52:55]
	v_mfma_f32_16x16x32_bf16 v[48:51], v[142:145], v[166:169], v[48:51]
	v_mfma_f32_16x16x32_bf16 v[44:47], v[134:137], v[174:177], v[44:47]
	v_mfma_f32_16x16x32_bf16 v[36:39], v[142:145], v[174:177], v[36:39]
	v_mfma_f32_16x16x32_bf16 v[28:31], v[134:137], v[194:197], v[28:31]
	v_mfma_f32_16x16x32_bf16 v[20:23], v[142:145], v[194:197], v[20:23]
	v_mfma_f32_16x16x32_bf16 v[12:15], v[134:137], v[202:205], v[12:15]
	v_mfma_f32_16x16x32_bf16 v[4:7], v[142:145], v[202:205], v[4:7]
	v_mfma_f32_16x16x32_bf16 v[52:55], v[138:141], v[170:173], v[52:55]
	v_mfma_f32_16x16x32_bf16 v[48:51], v[146:149], v[170:173], v[48:51]
	v_mfma_f32_16x16x32_bf16 v[44:47], v[138:141], v[178:181], v[44:47]
	v_mfma_f32_16x16x32_bf16 v[36:39], v[146:149], v[178:181], v[36:39]
	v_mfma_f32_16x16x32_bf16 v[28:31], v[138:141], v[198:201], v[28:31]
	v_mfma_f32_16x16x32_bf16 v[20:23], v[146:149], v[198:201], v[20:23]
	v_mfma_f32_16x16x32_bf16 v[12:15], v[138:141], v[206:209], v[12:15]
	v_mfma_f32_16x16x32_bf16 v[4:7], v[146:149], v[206:209], v[4:7]
	s_setprio 0
	s_barrier
	s_add_u32 s36, s36, 0xb0080
	s_addc_u32 s37, s37, 0
	s_mov_b32 m0, s65
	v_lshl_add_u64 v[134:135], s[36:37], 0, v[156:157]
	global_load_lds_dwordx4 v[134:135], off
	s_mov_b32 m0, s66
	v_lshl_add_u64 v[134:135], s[36:37], 0, v[160:161]
	global_load_lds_dwordx4 v[134:135], off
	s_waitcnt vmcnt(6)
	s_barrier
	s_setprio 1
	v_mfma_f32_16x16x32_bf16 v[60:63], v[210:213], v[166:169], v[60:63]
	v_mfma_f32_16x16x32_bf16 v[56:59], v[222:225], v[166:169], v[56:59]
	v_mfma_f32_16x16x32_bf16 v[40:43], v[210:213], v[174:177], v[40:43]
	v_mfma_f32_16x16x32_bf16 v[32:35], v[222:225], v[174:177], v[32:35]
	v_mfma_f32_16x16x32_bf16 v[24:27], v[210:213], v[194:197], v[24:27]
	v_mfma_f32_16x16x32_bf16 v[16:19], v[222:225], v[194:197], v[16:19]
	v_mfma_f32_16x16x32_bf16 v[8:11], v[210:213], v[202:205], v[8:11]
	v_mfma_f32_16x16x32_bf16 v[0:3], v[222:225], v[202:205], v[0:3]
	v_mfma_f32_16x16x32_bf16 v[60:63], v[214:217], v[170:173], v[60:63]
	v_mfma_f32_16x16x32_bf16 v[56:59], v[226:229], v[170:173], v[56:59]
	v_mfma_f32_16x16x32_bf16 v[40:43], v[214:217], v[178:181], v[40:43]
	v_mfma_f32_16x16x32_bf16 v[32:35], v[226:229], v[178:181], v[32:35]
	v_mfma_f32_16x16x32_bf16 v[24:27], v[214:217], v[198:201], v[24:27]
	v_mfma_f32_16x16x32_bf16 v[16:19], v[226:229], v[198:201], v[16:19]
	v_mfma_f32_16x16x32_bf16 v[8:11], v[214:217], v[206:209], v[8:11]
	v_mfma_f32_16x16x32_bf16 v[0:3], v[226:229], v[206:209], v[0:3]
	s_setprio 0
	s_add_i32 s67, s67, 2
	s_add_u32 s34, s34, 0x100
	s_addc_u32 s35, s35, 0
	s_cmp_gt_u32 s67, 39
	s_barrier
	s_cbranch_scc0 .LBB0_357
	ds_read_b128 v[134:137], v190
	ds_read_b128 v[138:141], v190 offset:1024
	ds_read_b128 v[142:145], v190 offset:2048
	ds_read_b128 v[146:149], v190 offset:3072
	s_mov_b32 m0, s54
	v_lshl_add_u64 v[150:151], v[128:129], 0, s[34:35]
	ds_read_b128 v[166:169], v191
	ds_read_b128 v[170:173], v191 offset:1024
	ds_read_b128 v[174:177], v191 offset:2048
	ds_read_b128 v[178:181], v191 offset:3072
	ds_read_b128 v[194:197], v191 offset:4096
	ds_read_b128 v[198:201], v191 offset:5120
	ds_read_b128 v[202:205], v191 offset:6144
	ds_read_b128 v[206:209], v191 offset:7168
	global_load_lds_dwordx4 v[150:151], off
	s_mov_b32 m0, s55
	v_lshl_add_u64 v[150:151], v[130:131], 0, s[34:35]
	global_load_lds_dwordx4 v[150:151], off
	s_waitcnt lgkmcnt(8)
	s_barrier
	s_waitcnt lgkmcnt(0)
	s_setprio 1
	v_mfma_f32_16x16x32_bf16 v[116:119], v[134:137], v[166:169], v[116:119]
	s_add_i32 s36, s34, 0xfff50080
	v_mfma_f32_16x16x32_bf16 v[112:115], v[142:145], v[166:169], v[112:115]
	s_cmp_eq_u32 s67, 40
	v_mfma_f32_16x16x32_bf16 v[108:111], v[134:137], v[174:177], v[108:111]
	s_cselect_b32 s69, s27, s29
	v_mfma_f32_16x16x32_bf16 v[104:107], v[142:145], v[174:177], v[104:107]
	s_cselect_b32 s68, s26, s28
	v_mfma_f32_16x16x32_bf16 v[92:95], v[134:137], v[194:197], v[92:95]
	s_cselect_b32 s37, s9, s31
	v_mfma_f32_16x16x32_bf16 v[88:91], v[142:145], v[194:197], v[88:91]
	s_cselect_b32 s70, s8, s30
	v_mfma_f32_16x16x32_bf16 v[76:79], v[134:137], v[202:205], v[76:79]
	v_mfma_f32_16x16x32_bf16 v[72:75], v[142:145], v[202:205], v[72:75]
	v_mfma_f32_16x16x32_bf16 v[116:119], v[138:141], v[170:173], v[116:119]
	v_mfma_f32_16x16x32_bf16 v[112:115], v[146:149], v[170:173], v[112:115]
	v_mfma_f32_16x16x32_bf16 v[108:111], v[138:141], v[178:181], v[108:111]
	v_mfma_f32_16x16x32_bf16 v[104:107], v[146:149], v[178:181], v[104:107]
	v_mfma_f32_16x16x32_bf16 v[92:95], v[138:141], v[198:201], v[92:95]
	v_mfma_f32_16x16x32_bf16 v[88:91], v[146:149], v[198:201], v[88:91]
	v_mfma_f32_16x16x32_bf16 v[76:79], v[138:141], v[206:209], v[76:79]
	v_mfma_f32_16x16x32_bf16 v[72:75], v[146:149], v[206:209], v[72:75]
	s_setprio 0
	s_barrier
	s_cselect_b32 s71, 0, s36
	s_add_u32 s36, s70, s71
	s_addc_u32 s37, s37, 0
	s_mov_b32 m0, s56
	v_lshl_add_u64 v[150:151], s[36:37], 0, v[156:157]
	ds_read_b128 v[210:213], v192
	ds_read_b128 v[214:217], v192 offset:1024
	ds_read_b128 v[222:225], v192 offset:2048
	ds_read_b128 v[226:229], v192 offset:3072
	global_load_lds_dwordx4 v[150:151], off
	s_mov_b32 m0, s57
	v_lshl_add_u64 v[182:183], s[36:37], 0, v[160:161]
	global_load_lds_dwordx4 v[182:183], off
	s_barrier
;     __device__ __forceinline__ void epi(const f32x4 (&acc)[2][2][4][2], const Unit& u, int wr, int wc, int fr, int fq) const {
;     ...
;                 for (int bj = 0; bj < 2; ++bj) xo[m][bj] = *(const u32x4*)(xb + (size_t)(row0 + ai * 128 + m * 16) * D + col0 + bj * 128);
	s_waitcnt lgkmcnt(0)
	s_setprio 1
	v_mfma_f32_16x16x32_bf16 v[124:127], v[210:213], v[166:169], v[124:127]
	v_mfma_f32_16x16x32_bf16 v[120:123], v[222:225], v[166:169], v[120:123]
	v_mfma_f32_16x16x32_bf16 v[100:103], v[210:213], v[174:177], v[100:103]
	v_mfma_f32_16x16x32_bf16 v[96:99], v[222:225], v[174:177], v[96:99]
	v_mfma_f32_16x16x32_bf16 v[84:87], v[210:213], v[194:197], v[84:87]
	v_mfma_f32_16x16x32_bf16 v[80:83], v[222:225], v[194:197], v[80:83]
	v_mfma_f32_16x16x32_bf16 v[68:71], v[210:213], v[202:205], v[68:71]
	v_mfma_f32_16x16x32_bf16 v[64:67], v[222:225], v[202:205], v[64:67]
	v_mfma_f32_16x16x32_bf16 v[124:127], v[214:217], v[170:173], v[124:127]
	v_mfma_f32_16x16x32_bf16 v[120:123], v[226:229], v[170:173], v[120:123]
	v_mfma_f32_16x16x32_bf16 v[100:103], v[214:217], v[178:181], v[100:103]
	v_mfma_f32_16x16x32_bf16 v[96:99], v[226:229], v[178:181], v[96:99]
	v_mfma_f32_16x16x32_bf16 v[84:87], v[214:217], v[198:201], v[84:87]
	v_mfma_f32_16x16x32_bf16 v[80:83], v[226:229], v[198:201], v[80:83]
	v_mfma_f32_16x16x32_bf16 v[68:71], v[214:217], v[206:209], v[68:71]
	v_mfma_f32_16x16x32_bf16 v[64:67], v[226:229], v[206:209], v[64:67]
	s_setprio 0
	s_add_u32 s68, s68, s71
	s_addc_u32 s69, s69, 0
	s_mov_b32 m0, s46
	v_lshl_add_u64 v[218:219], s[68:69], 0, v[154:155]
	s_barrier
	ds_read_b128 v[166:169], v191 offset:16384
	ds_read_b128 v[170:173], v191 offset:17408
	ds_read_b128 v[174:177], v191 offset:18432
	ds_read_b128 v[178:181], v191 offset:19456
	ds_read_b128 v[194:197], v191 offset:20480
	ds_read_b128 v[198:201], v191 offset:21504
	ds_read_b128 v[202:205], v191 offset:22528
	ds_read_b128 v[206:209], v191 offset:23552
	global_load_lds_dwordx4 v[218:219], off
	s_mov_b32 m0, s47
	v_lshl_add_u64 v[230:231], s[68:69], 0, v[158:159]
	global_load_lds_dwordx4 v[230:231], off
	s_barrier
	s_waitcnt lgkmcnt(0)
	s_setprio 1
	v_mfma_f32_16x16x32_bf16 v[52:55], v[134:137], v[166:169], v[52:55]
	v_mfma_f32_16x16x32_bf16 v[48:51], v[142:145], v[166:169], v[48:51]
	v_mfma_f32_16x16x32_bf16 v[44:47], v[134:137], v[174:177], v[44:47]
	v_mfma_f32_16x16x32_bf16 v[36:39], v[142:145], v[174:177], v[36:39]
	v_mfma_f32_16x16x32_bf16 v[28:31], v[134:137], v[194:197], v[28:31]
	v_mfma_f32_16x16x32_bf16 v[20:23], v[142:145], v[194:197], v[20:23]
	v_mfma_f32_16x16x32_bf16 v[12:15], v[134:137], v[202:205], v[12:15]
	v_mfma_f32_16x16x32_bf16 v[4:7], v[142:145], v[202:205], v[4:7]
	v_mfma_f32_16x16x32_bf16 v[52:55], v[138:141], v[170:173], v[52:55]
	v_mfma_f32_16x16x32_bf16 v[48:51], v[146:149], v[170:173], v[48:51]
	v_mfma_f32_16x16x32_bf16 v[44:47], v[138:141], v[178:181], v[44:47]
	v_mfma_f32_16x16x32_bf16 v[36:39], v[146:149], v[178:181], v[36:39]
	v_mfma_f32_16x16x32_bf16 v[28:31], v[138:141], v[198:201], v[28:31]
	v_mfma_f32_16x16x32_bf16 v[20:23], v[146:149], v[198:201], v[20:23]
	v_mfma_f32_16x16x32_bf16 v[12:15], v[138:141], v[206:209], v[12:15]
	v_mfma_f32_16x16x32_bf16 v[4:7], v[146:149], v[206:209], v[4:7]
	s_setprio 0
	s_barrier
	s_add_u32 s70, s36, 0xb0000
	s_addc_u32 s71, s37, 0
	s_mov_b32 m0, s0
	v_lshl_add_u64 v[134:135], s[70:71], 0, v[156:157]
	global_load_lds_dwordx4 v[134:135], off
	s_mov_b32 m0, s62
	v_lshl_add_u64 v[134:135], s[70:71], 0, v[160:161]
	global_load_lds_dwordx4 v[134:135], off
	s_waitcnt vmcnt(6)
	s_barrier
	s_setprio 1
	v_mfma_f32_16x16x32_bf16 v[60:63], v[210:213], v[166:169], v[60:63]
	v_lshl_or_b32 v248, s40, 8, v189
	v_mfma_f32_16x16x32_bf16 v[56:59], v[222:225], v[166:169], v[56:59]
	v_lshl_add_u32 v250, s61, 8, v153
	v_mfma_f32_16x16x32_bf16 v[40:43], v[210:213], v[174:177], v[40:43]
	v_ashrrev_i32_e32 v249, 31, v248
	v_mfma_f32_16x16x32_bf16 v[32:35], v[222:225], v[174:177], v[32:35]
	v_lshlrev_b64 v[248:249], 1, v[248:249]
	v_mfma_f32_16x16x32_bf16 v[24:27], v[210:213], v[194:197], v[24:27]
	v_ashrrev_i32_e32 v251, 31, v250
	v_mfma_f32_16x16x32_bf16 v[16:19], v[222:225], v[194:197], v[16:19]
	v_lshl_add_u64 v[248:249], s[20:21], 0, v[248:249]
	v_mfma_f32_16x16x32_bf16 v[8:11], v[210:213], v[202:205], v[8:11]
	v_lshlrev_b64 v[250:251], 11, v[250:251]
	v_mfma_f32_16x16x32_bf16 v[0:3], v[222:225], v[202:205], v[0:3]
	v_lshl_add_u64 v[252:253], v[248:249], 0, v[250:251]
	v_mfma_f32_16x16x32_bf16 v[60:63], v[214:217], v[170:173], v[60:63]
	global_load_dwordx4 v[232:235], v[252:253], off
	v_mfma_f32_16x16x32_bf16 v[56:59], v[226:229], v[170:173], v[56:59]
	global_load_dwordx4 v[236:239], v[252:253], off offset:256
	v_mfma_f32_16x16x32_bf16 v[40:43], v[214:217], v[178:181], v[40:43]
	v_mov_b32_e32 v250, 0x8000
	v_mfma_f32_16x16x32_bf16 v[32:35], v[226:229], v[178:181], v[32:35]
	v_mov_b32_e32 v251, 0
	v_mfma_f32_16x16x32_bf16 v[24:27], v[214:217], v[198:201], v[24:27]
	v_lshl_add_u64 v[250:251], v[252:253], 0, v[250:251]
	v_mfma_f32_16x16x32_bf16 v[16:19], v[226:229], v[198:201], v[16:19]
	global_load_dwordx4 v[240:243], v[250:251], off
	v_mfma_f32_16x16x32_bf16 v[8:11], v[214:217], v[206:209], v[8:11]
	global_load_dwordx4 v[244:247], v[250:251], off offset:256
	v_mfma_f32_16x16x32_bf16 v[0:3], v[226:229], v[206:209], v[0:3]
	s_setprio 0
	s_barrier
	ds_read_b128 v[134:137], v132
	ds_read_b128 v[138:141], v132 offset:1024
	ds_read_b128 v[142:145], v132 offset:2048
	ds_read_b128 v[146:149], v132 offset:3072
	s_add_u32 s68, s68, 0xb0000
	s_addc_u32 s69, s69, 0
	s_mov_b32 m0, s48
	v_lshl_add_u64 v[210:211], s[68:69], 0, v[154:155]
	ds_read_b128 v[166:169], v191 offset:32768
	ds_read_b128 v[170:173], v191 offset:33792
	ds_read_b128 v[174:177], v191 offset:34816
	ds_read_b128 v[178:181], v191 offset:35840
	ds_read_b128 v[194:197], v191 offset:36864
	ds_read_b128 v[198:201], v191 offset:37888
	ds_read_b128 v[202:205], v191 offset:38912
	ds_read_b128 v[206:209], v191 offset:39936
	global_load_lds_dwordx4 v[210:211], off
	s_mov_b32 m0, s49
	v_lshl_add_u64 v[210:211], s[68:69], 0, v[158:159]
	global_load_lds_dwordx4 v[210:211], off
	s_waitcnt lgkmcnt(8)
	s_barrier
	s_waitcnt lgkmcnt(0)
	s_setprio 1
	v_mfma_f32_16x16x32_bf16 v[116:119], v[134:137], v[166:169], v[116:119]
	v_mfma_f32_16x16x32_bf16 v[112:115], v[142:145], v[166:169], v[112:115]
	v_mfma_f32_16x16x32_bf16 v[108:111], v[134:137], v[174:177], v[108:111]
	v_mfma_f32_16x16x32_bf16 v[104:107], v[142:145], v[174:177], v[104:107]
	v_mfma_f32_16x16x32_bf16 v[92:95], v[134:137], v[194:197], v[92:95]
	v_mfma_f32_16x16x32_bf16 v[88:91], v[142:145], v[194:197], v[88:91]
	v_mfma_f32_16x16x32_bf16 v[76:79], v[134:137], v[202:205], v[76:79]
	v_mfma_f32_16x16x32_bf16 v[72:75], v[142:145], v[202:205], v[72:75]
	v_mfma_f32_16x16x32_bf16 v[116:119], v[138:141], v[170:173], v[116:119]
	v_mfma_f32_16x16x32_bf16 v[112:115], v[146:149], v[170:173], v[112:115]
	v_mfma_f32_16x16x32_bf16 v[108:111], v[138:141], v[178:181], v[108:111]
	v_mfma_f32_16x16x32_bf16 v[104:107], v[146:149], v[178:181], v[104:107]
	v_mfma_f32_16x16x32_bf16 v[92:95], v[138:141], v[198:201], v[92:95]
	v_mfma_f32_16x16x32_bf16 v[88:91], v[146:149], v[198:201], v[88:91]
	v_mfma_f32_16x16x32_bf16 v[76:79], v[138:141], v[206:209], v[76:79]
	v_mfma_f32_16x16x32_bf16 v[72:75], v[146:149], v[206:209], v[72:75]
	s_setprio 0
	s_barrier
	s_mov_b32 m0, s63
	v_lshl_add_u64 v[150:151], v[150:151], 0, s[10:11]
	ds_read_b128 v[210:213], v133
	ds_read_b128 v[214:217], v133 offset:1024
	ds_read_b128 v[222:225], v133 offset:2048
	ds_read_b128 v[226:229], v133 offset:3072
	global_load_lds_dwordx4 v[150:151], off
	s_mov_b32 m0, s64
	v_lshl_add_u64 v[150:151], v[182:183], 0, s[10:11]
	global_load_lds_dwordx4 v[150:151], off
	s_barrier
	s_waitcnt lgkmcnt(0)
	s_setprio 1
	v_mfma_f32_16x16x32_bf16 v[124:127], v[210:213], v[166:169], v[124:127]
	v_mfma_f32_16x16x32_bf16 v[120:123], v[222:225], v[166:169], v[120:123]
	v_mfma_f32_16x16x32_bf16 v[100:103], v[210:213], v[174:177], v[100:103]
	v_mfma_f32_16x16x32_bf16 v[96:99], v[222:225], v[174:177], v[96:99]
	v_mfma_f32_16x16x32_bf16 v[84:87], v[210:213], v[194:197], v[84:87]
	v_mfma_f32_16x16x32_bf16 v[80:83], v[222:225], v[194:197], v[80:83]
	v_mfma_f32_16x16x32_bf16 v[68:71], v[210:213], v[202:205], v[68:71]
	v_mfma_f32_16x16x32_bf16 v[64:67], v[222:225], v[202:205], v[64:67]
	v_mfma_f32_16x16x32_bf16 v[124:127], v[214:217], v[170:173], v[124:127]
	v_mfma_f32_16x16x32_bf16 v[120:123], v[226:229], v[170:173], v[120:123]
	v_mfma_f32_16x16x32_bf16 v[100:103], v[214:217], v[178:181], v[100:103]
	v_mfma_f32_16x16x32_bf16 v[96:99], v[226:229], v[178:181], v[96:99]
	v_mfma_f32_16x16x32_bf16 v[84:87], v[214:217], v[198:201], v[84:87]
	v_mfma_f32_16x16x32_bf16 v[80:83], v[226:229], v[198:201], v[80:83]
	v_mfma_f32_16x16x32_bf16 v[68:71], v[214:217], v[206:209], v[68:71]
	v_mfma_f32_16x16x32_bf16 v[64:67], v[226:229], v[206:209], v[64:67]
	s_setprio 0
	s_mov_b32 m0, s51
	v_lshl_add_u64 v[150:151], v[218:219], 0, s[10:11]
	s_barrier
	ds_read_b128 v[166:169], v191 offset:49152
	ds_read_b128 v[170:173], v191 offset:50176
	ds_read_b128 v[174:177], v191 offset:51200
	ds_read_b128 v[178:181], v191 offset:52224
	ds_read_b128 v[194:197], v191 offset:53248
	ds_read_b128 v[198:201], v191 offset:54272
	ds_read_b128 v[202:205], v191 offset:55296
	ds_read_b128 v[206:209], v191 offset:56320
	global_load_lds_dwordx4 v[150:151], off
	s_mov_b32 m0, s52
	v_lshl_add_u64 v[150:151], v[230:231], 0, s[10:11]
	global_load_lds_dwordx4 v[150:151], off
	s_barrier
	s_waitcnt lgkmcnt(0)
	s_setprio 1
	v_mfma_f32_16x16x32_bf16 v[52:55], v[134:137], v[166:169], v[52:55]
	v_mfma_f32_16x16x32_bf16 v[48:51], v[142:145], v[166:169], v[48:51]
	v_mfma_f32_16x16x32_bf16 v[44:47], v[134:137], v[174:177], v[44:47]
	v_mfma_f32_16x16x32_bf16 v[36:39], v[142:145], v[174:177], v[36:39]
	v_mfma_f32_16x16x32_bf16 v[28:31], v[134:137], v[194:197], v[28:31]
	v_mfma_f32_16x16x32_bf16 v[20:23], v[142:145], v[194:197], v[20:23]
	v_mfma_f32_16x16x32_bf16 v[12:15], v[134:137], v[202:205], v[12:15]
	v_mfma_f32_16x16x32_bf16 v[4:7], v[142:145], v[202:205], v[4:7]
	v_mfma_f32_16x16x32_bf16 v[52:55], v[138:141], v[170:173], v[52:55]
	v_mfma_f32_16x16x32_bf16 v[48:51], v[146:149], v[170:173], v[48:51]
	v_mfma_f32_16x16x32_bf16 v[44:47], v[138:141], v[178:181], v[44:47]
	v_mfma_f32_16x16x32_bf16 v[36:39], v[146:149], v[178:181], v[36:39]
	v_mfma_f32_16x16x32_bf16 v[28:31], v[138:141], v[198:201], v[28:31]
	v_mfma_f32_16x16x32_bf16 v[20:23], v[146:149], v[198:201], v[20:23]
	v_mfma_f32_16x16x32_bf16 v[12:15], v[138:141], v[206:209], v[12:15]
	v_mfma_f32_16x16x32_bf16 v[4:7], v[146:149], v[206:209], v[4:7]
	s_setprio 0
	s_barrier
	s_add_u32 s36, s36, 0xb0080
	s_addc_u32 s37, s37, 0
	s_mov_b32 m0, s65
	v_lshl_add_u64 v[134:135], s[36:37], 0, v[156:157]
	global_load_lds_dwordx4 v[134:135], off
	s_mov_b32 m0, s66
	v_lshl_add_u64 v[134:135], s[36:37], 0, v[160:161]
	global_load_lds_dwordx4 v[134:135], off
	s_waitcnt vmcnt(6)
	s_barrier
	s_setprio 1
	v_mfma_f32_16x16x32_bf16 v[60:63], v[210:213], v[166:169], v[60:63]
	v_mfma_f32_16x16x32_bf16 v[56:59], v[222:225], v[166:169], v[56:59]
	v_mfma_f32_16x16x32_bf16 v[40:43], v[210:213], v[174:177], v[40:43]
	v_mfma_f32_16x16x32_bf16 v[32:35], v[222:225], v[174:177], v[32:35]
	v_mfma_f32_16x16x32_bf16 v[24:27], v[210:213], v[194:197], v[24:27]
	v_mfma_f32_16x16x32_bf16 v[16:19], v[222:225], v[194:197], v[16:19]
	v_mfma_f32_16x16x32_bf16 v[8:11], v[210:213], v[202:205], v[8:11]
	v_mfma_f32_16x16x32_bf16 v[0:3], v[222:225], v[202:205], v[0:3]
	v_mfma_f32_16x16x32_bf16 v[60:63], v[214:217], v[170:173], v[60:63]
	v_mfma_f32_16x16x32_bf16 v[56:59], v[226:229], v[170:173], v[56:59]
	v_mfma_f32_16x16x32_bf16 v[40:43], v[214:217], v[178:181], v[40:43]
	v_mfma_f32_16x16x32_bf16 v[32:35], v[226:229], v[178:181], v[32:35]
	v_mfma_f32_16x16x32_bf16 v[24:27], v[214:217], v[198:201], v[24:27]
	v_mfma_f32_16x16x32_bf16 v[16:19], v[226:229], v[198:201], v[16:19]
	v_mfma_f32_16x16x32_bf16 v[8:11], v[214:217], v[206:209], v[8:11]
	v_mfma_f32_16x16x32_bf16 v[0:3], v[226:229], v[206:209], v[0:3]
	s_setprio 0
	s_add_i32 s67, s67, 2
	s_add_u32 s34, s34, 0x100
	s_addc_u32 s35, s35, 0
	s_cmp_gt_u32 s67, 41
	s_barrier
; __device__ __forceinline__ unsigned pk2(float lo, float hi) { unsigned r; asm volatile("v_cvt_pk_bf16_f32 %0, %1, %2" : "=v"(r) : "v"(lo), "v"(hi)); return r; }
; __device__ __forceinline__ unsigned pk2(float lo, float hi) { return f2bf(lo) | (f2bf(hi) << 16); }
;     __device__ __forceinline__ void epi(const f32x4 (&acc)[2][2][4][2], const Unit& u, int wr, int wc, int fr, int fq) const {
;     ...
;         for (int ai = 0; ai < 2; ++ai) {
;             u32x4 xo[4][2];
; #pragma unroll
;             for (int m = 0; m < 4; ++m)
; #pragma unroll
;                 for (int bj = 0; bj < 2; ++bj) xo[m][bj] = *(const u32x4*)(xb + (size_t)(row0 + ai * 128 + m * 16) * D + col0 + bj * 128);
; #pragma unroll
;             for (int m = 0; m < 4; ++m) {
;                 const int row = row0 + ai * 128 + m * 16; const size_t off = (size_t)row * D + col0; float ss = 0.f;
; #pragma unroll
;                 for (int bj = 0; bj < 2; ++bj) {
;                     const u32x4 o = xo[m][bj]; const f32x4 a0v = acc[ai][bj][m][0], a1v = acc[ai][bj][m][1];
;                     const float v0 = bf_lo(o.x) + coef * a0v[0], v1 = bf_hi(o.x) + coef * a0v[1], v2 = bf_lo(o.y) + coef * a0v[2], v3 = bf_hi(o.y) + coef * a0v[3];
;                     const float v4 = bf_lo(o.z) + coef * a1v[0], v5 = bf_hi(o.z) + coef * a1v[1], v6 = bf_lo(o.w) + coef * a1v[2], v7 = bf_hi(o.w) + coef * a1v[3];
;                     u32x4 w; w.x = pk2(v0, v1); w.y = pk2(v2, v3); w.z = pk2(v4, v5); w.w = pk2(v6, v7);
;                     *(u32x4*)(xb + off + bj * 128) = w;
;                     ss += ((v0 * v0 + v1 * v1) + (v2 * v2 + v3 * v3)) + ((v4 * v4 + v5 * v5) + (v6 * v6 + v7 * v7));
;                 }
	v_lshl_or_b32 v166, s40, 8, v189
	v_lshl_add_u32 v170, s61, 8, v153
	v_ashrrev_i32_e32 v167, 31, v166
	v_lshlrev_b64 v[202:203], 1, v[166:167]
	v_ashrrev_i32_e32 v171, 31, v170
	v_lshl_add_u64 v[168:169], s[20:21], 0, v[202:203]
	v_lshlrev_b64 v[204:205], 11, v[170:171]
	v_lshl_add_u64 v[128:129], v[168:169], 0, v[204:205]
	v_mov_b32_e32 v218, 0x40000
	v_mov_b32_e32 v219, 0
	v_lshl_add_u64 v[216:217], v[128:129], 0, v[218:219]
	v_mov_b32_e32 v218, 0x8000
	s_waitcnt vmcnt(8)
	v_mov_b64_e32 v[194:195], v[232:233]
	v_mov_b64_e32 v[196:197], v[234:235]
	v_mov_b64_e32 v[198:199], v[236:237]
	v_mov_b64_e32 v[200:201], v[238:239]
	v_or_b32_e32 v180, 16, v170
	v_or_b32_e32 v176, 32, v170
	v_or_b32_e32 v172, 48, v170
	v_ashrrev_i32_e32 v181, 31, v180
	v_ashrrev_i32_e32 v177, 31, v176
	v_ashrrev_i32_e32 v173, 31, v172
	v_lshlrev_b64 v[182:183], 11, v[180:181]
	v_lshlrev_b64 v[178:179], 11, v[176:177]
	v_lshlrev_b64 v[174:175], 11, v[172:173]
	v_lshl_add_u64 v[128:129], v[168:169], 0, v[182:183]
	v_lshl_add_u64 v[130:131], v[168:169], 0, v[178:179]
	v_lshl_add_u64 v[206:207], v[168:169], 0, v[174:175]
	v_mov_b64_e32 v[148:149], v[240:241]
	v_mov_b64_e32 v[150:151], v[242:243]
	v_mov_b64_e32 v[144:145], v[244:245]
	v_mov_b64_e32 v[146:147], v[246:247]
	global_load_dwordx4 v[140:143], v[130:131], off
	global_load_dwordx4 v[136:139], v[130:131], off offset:256
	global_load_dwordx4 v[132:135], v[206:207], off
	s_nop 0
	global_load_dwordx4 v[128:131], v[206:207], off offset:256
	global_load_dwordx4 v[222:225], v[216:217], off
	global_load_dwordx4 v[226:229], v[216:217], off offset:256
	v_lshl_add_u64 v[216:217], v[216:217], 0, v[218:219]
	global_load_dwordx4 v[230:233], v[216:217], off
	global_load_dwordx4 v[234:237], v[216:217], off offset:256
	v_lshl_add_u64 v[216:217], v[216:217], 0, v[218:219]
	global_load_dwordx4 v[238:241], v[216:217], off
	global_load_dwordx4 v[242:245], v[216:217], off offset:256
	v_lshl_add_u64 v[216:217], v[216:217], 0, v[218:219]
	global_load_dwordx4 v[246:249], v[216:217], off
	global_load_dwordx4 v[250:253], v[216:217], off offset:256
	v_and_b32_e32 v206, 64, v193
	v_xor_b32_e32 v208, 16, v193
	v_add_u32_e32 v206, 64, v206
	v_cmp_lt_i32_e32 vcc, v208, v206
	v_lshlrev_b32_e32 v209, 16, v195
	v_cndmask_b32_e32 v207, v193, v208, vcc
	v_lshlrev_b32_e32 v208, 16, v194
	v_and_b32_e32 v194, 0xffff0000, v194
	v_and_b32_e32 v195, 0xffff0000, v195
	v_lshlrev_b32_e32 v210, 16, v196
	v_and_b32_e32 v196, 0xffff0000, v196
	v_lshlrev_b32_e32 v211, 16, v197
	v_and_b32_e32 v197, 0xffff0000, v197
	v_lshlrev_b32_e32 v212, 16, v198
	v_and_b32_e32 v198, 0xffff0000, v198
	v_lshlrev_b32_e32 v213, 16, v199
	v_and_b32_e32 v199, 0xffff0000, v199
	v_lshlrev_b32_e32 v214, 16, v200
	v_and_b32_e32 v200, 0xffff0000, v200
	v_lshlrev_b32_e32 v215, 16, v201
	v_and_b32_e32 v201, 0xffff0000, v201
	v_fmac_f32_e32 v194, 0.5, v117
	v_fmac_f32_e32 v195, 0.5, v119
	v_fmac_f32_e32 v196, 0.5, v113
	v_fmac_f32_e32 v197, 0.5, v115
	v_fmac_f32_e32 v198, 0.5, v125
	v_fmac_f32_e32 v199, 0.5, v127
	v_fmac_f32_e32 v200, 0.5, v121
	v_fmac_f32_e32 v201, 0.5, v123
	v_fmac_f32_e32 v208, 0.5, v116
	v_fmac_f32_e32 v209, 0.5, v118
	v_fmac_f32_e32 v210, 0.5, v112
	v_fmac_f32_e32 v211, 0.5, v114
	v_fmac_f32_e32 v212, 0.5, v124
	v_fmac_f32_e32 v213, 0.5, v126
	v_fmac_f32_e32 v214, 0.5, v120
	v_fmac_f32_e32 v215, 0.5, v122
	v_mul_f32_e32 v112, v194, v194
	v_mul_f32_e32 v113, v195, v195
	v_mul_f32_e32 v118, v196, v196
	v_mul_f32_e32 v119, v197, v197
	v_mul_f32_e32 v120, v198, v198
	v_mul_f32_e32 v121, v199, v199
	v_mul_f32_e32 v122, v200, v200
	v_mul_f32_e32 v123, v201, v201
	v_fmac_f32_e32 v112, v208, v208
	v_fmac_f32_e32 v113, v209, v209
	v_fmac_f32_e32 v118, v210, v210
	v_fmac_f32_e32 v119, v211, v211
	v_fmac_f32_e32 v120, v212, v212
	v_fmac_f32_e32 v121, v213, v213
	v_fmac_f32_e32 v122, v214, v214
	v_fmac_f32_e32 v123, v215, v215
	v_add_f32_e32 v112, v112, v113
	v_add_f32_e32 v113, v118, v119
	v_add_f32_e32 v118, v120, v121
	v_add_f32_e32 v119, v122, v123
	v_add_f32_e32 v112, v112, v113
	v_add_f32_e32 v113, v118, v119
	v_add_f32_e32 v113, v112, v113
	v_lshlrev_b32_e32 v112, 2, v207
	ds_bpermute_b32 v122, v112, v113
	v_lshl_add_u64 v[118:119], s[20:21], 0, v[204:205]
	v_cvt_pk_bf16_f32 v114, v208, v194
	v_lshl_add_u64 v[120:121], v[118:119], 0, v[202:203]
	v_cvt_pk_bf16_f32 v115, v209, v195
	v_cvt_pk_bf16_f32 v116, v210, v196
	v_cvt_pk_bf16_f32 v117, v211, v197
	global_store_dwordx4 v[120:121], v[114:117], off
	s_waitcnt lgkmcnt(0)
	s_nop 0
	v_add_f32_e32 v114, v113, v122
	v_xor_b32_e32 v113, 32, v193
	v_cmp_lt_i32_e32 vcc, v113, v206
	v_cvt_pk_bf16_f32 v116, v212, v198
	v_cvt_pk_bf16_f32 v117, v213, v199
	v_cvt_pk_bf16_f32 v118, v214, v200
	v_cvt_pk_bf16_f32 v119, v215, v201
	global_store_dwordx4 v[120:121], v[116:119], off offset:256
	s_nop 0
	v_cndmask_b32_e32 v113, v193, v113, vcc
	v_lshlrev_b32_e32 v113, 2, v113
	ds_bpermute_b32 v115, v113, v114
	s_and_saveexec_b64 s[28:29], s[6:7]
	s_cbranch_execz .LBB0_360
	s_waitcnt lgkmcnt(0)
	v_add_f32_e32 v116, v114, v115
	s_lshl_b32 s30, s40, 2
	v_lshlrev_b64 v[114:115], 7, v[170:171]
	s_ashr_i32 s31, s30, 31
	v_lshl_add_u64 v[114:115], s[2:3], 0, v[114:115]
	v_lshl_add_u64 v[114:115], s[30:31], 2, v[114:115]
	s_lshl_b32 s0, s50, 2
	v_lshl_add_u64 v[114:115], v[114:115], 0, s[0:1]
	global_store_dword v[114:115], v116, off

; __device__ __forceinline__ unsigned pk2(float lo, float hi) { unsigned r; asm volatile("v_cvt_pk_bf16_f32 %0, %1, %2" : "=v"(r) : "v"(lo), "v"(hi)); return r; }
; __device__ __forceinline__ unsigned pk2(float lo, float hi) { return f2bf(lo) | (f2bf(hi) << 16); }
;     __device__ __forceinline__ void epi(const f32x4 (&acc)[2][2][4][2], const Unit& u, int wr, int wc, int fr, int fq) const {
;     ...
;             for (int m = 0; m < 4; ++m) {
;                 const int row = row0 + ai * 128 + m * 16; const size_t off = (size_t)row * D + col0; float ss = 0.f;
; #pragma unroll
;                 for (int bj = 0; bj < 2; ++bj) {
;                     const u32x4 o = xo[m][bj]; const f32x4 a0v = acc[ai][bj][m][0], a1v = acc[ai][bj][m][1];
;                     const float v0 = bf_lo(o.x) + coef * a0v[0], v1 = bf_hi(o.x) + coef * a0v[1], v2 = bf_lo(o.y) + coef * a0v[2], v3 = bf_hi(o.y) + coef * a0v[3];
;                     const float v4 = bf_lo(o.z) + coef * a1v[0], v5 = bf_hi(o.z) + coef * a1v[1], v6 = bf_lo(o.w) + coef * a1v[2], v7 = bf_hi(o.w) + coef * a1v[3];
;                     u32x4 w; w.x = pk2(v0, v1); w.y = pk2(v2, v3); w.z = pk2(v4, v5); w.w = pk2(v6, v7);
;                     *(u32x4*)(xb + off + bj * 128) = w;
;                     ss += ((v0 * v0 + v1 * v1) + (v2 * v2 + v3 * v3)) + ((v4 * v4 + v5 * v5) + (v6 * v6 + v7 * v7));
;                 }
;                 ss += __shfl_xor(ss, 16); ss += __shfl_xor(ss, 32);
;                 if (fq == 0) rowss[(size_t)row * 32 + u.pn * 4 + wc] = ss;
.LBB0_362:
	s_or_b64 exec, exec, s[28:29]
	s_waitcnt vmcnt(12)
	v_lshlrev_b32_e32 v96, 16, v140
	v_fmac_f32_e32 v96, 0.5, v92
	v_and_b32_e32 v92, 0xffff0000, v140
	v_fmac_f32_e32 v92, 0.5, v93
	v_lshlrev_b32_e32 v93, 16, v141
	v_fmac_f32_e32 v93, 0.5, v94
	v_and_b32_e32 v94, 0xffff0000, v141
	v_fmac_f32_e32 v94, 0.5, v95
	v_lshlrev_b32_e32 v95, 16, v142
	s_waitcnt lgkmcnt(0)
	v_and_b32_e32 v97, 0xffff0000, v142
	v_fmac_f32_e32 v95, 0.5, v88
	v_fmac_f32_e32 v97, 0.5, v89
	v_and_b32_e32 v99, 0xffff0000, v143
	v_cvt_pk_bf16_f32 v88, v96, v92
	v_cvt_pk_bf16_f32 v89, v93, v94
	v_mul_f32_e32 v92, v92, v92
	v_mul_f32_e32 v94, v94, v94
	v_lshlrev_b32_e32 v98, 16, v143
	v_fmac_f32_e32 v99, 0.5, v91
	v_fmac_f32_e32 v92, v96, v96
	v_fmac_f32_e32 v94, v93, v93
	v_fmac_f32_e32 v98, 0.5, v90
	v_add_f32_e32 v92, v92, v94
	v_mul_f32_e32 v93, v97, v97
	v_mul_f32_e32 v94, v99, v99
	v_fmac_f32_e32 v93, v95, v95
	v_fmac_f32_e32 v94, v98, v98
	v_add_f32_e32 v93, v93, v94
	v_add_f32_e32 v92, v92, v93
	v_lshlrev_b32_e32 v93, 16, v136
	v_fmac_f32_e32 v93, 0.5, v84
	v_and_b32_e32 v84, 0xffff0000, v136
	v_and_b32_e32 v94, 0xffff0000, v137
	v_cvt_pk_bf16_f32 v90, v95, v97
	v_fmac_f32_e32 v84, 0.5, v85
	v_lshlrev_b32_e32 v85, 16, v137
	v_fmac_f32_e32 v94, 0.5, v87
	v_lshlrev_b32_e32 v95, 16, v138
	v_and_b32_e32 v96, 0xffff0000, v138
	v_cvt_pk_bf16_f32 v91, v98, v99
	v_fmac_f32_e32 v85, 0.5, v86
	v_fmac_f32_e32 v95, 0.5, v80
	v_fmac_f32_e32 v96, 0.5, v81
	v_and_b32_e32 v98, 0xffff0000, v139
	v_mul_f32_e32 v80, v84, v84
	v_mul_f32_e32 v81, v94, v94
	v_lshlrev_b32_e32 v97, 16, v139
	v_fmac_f32_e32 v98, 0.5, v83
	v_fmac_f32_e32 v80, v93, v93
	v_fmac_f32_e32 v81, v85, v85
	v_fmac_f32_e32 v97, 0.5, v82
	v_add_f32_e32 v80, v80, v81
	v_mul_f32_e32 v81, v96, v96
	v_mul_f32_e32 v82, v98, v98
	v_fmac_f32_e32 v81, v95, v95
	v_fmac_f32_e32 v82, v97, v97
	v_add_f32_e32 v81, v81, v82
	v_add_f32_e32 v80, v80, v81
	v_add_f32_e32 v83, v92, v80
	ds_bpermute_b32 v92, v112, v83
	v_lshl_add_u64 v[80:81], s[20:21], 0, v[178:179]
	v_lshl_add_u64 v[86:87], v[166:167], 1, v[80:81]
	global_store_dwordx4 v[86:87], v[88:91], off
	v_cvt_pk_bf16_f32 v82, v93, v84
	s_waitcnt lgkmcnt(0)
	v_add_f32_e32 v80, v83, v92
	ds_bpermute_b32 v81, v113, v80
	v_cvt_pk_bf16_f32 v83, v85, v94
	v_cvt_pk_bf16_f32 v84, v95, v96
	v_cvt_pk_bf16_f32 v85, v97, v98
	global_store_dwordx4 v[86:87], v[82:85], off offset:256
	s_and_saveexec_b64 s[28:29], s[6:7]
	s_cbranch_execz .LBB0_364
	s_waitcnt lgkmcnt(0)
	v_add_f32_e32 v82, v80, v81
	s_lshl_b32 s30, s40, 2
	v_lshlrev_b64 v[80:81], 7, v[176:177]
	s_ashr_i32 s31, s30, 31
	v_lshl_add_u64 v[80:81], s[2:3], 0, v[80:81]
	v_lshl_add_u64 v[80:81], s[30:31], 2, v[80:81]
	s_lshl_b32 s0, s50, 2
	v_lshl_add_u64 v[80:81], v[80:81], 0, s[0:1]
	global_store_dword v[80:81], v82, off

.LBB0_1906:
	ds_read_b128 v[134:137], v185
	ds_read_b128 v[138:141], v185 offset:1024
	ds_read_b128 v[142:145], v185 offset:2048
	ds_read_b128 v[146:149], v185 offset:3072
	s_mov_b32 m0, s45
	v_lshl_add_u64 v[150:151], v[128:129], 0, s[24:25]
	ds_read_b128 v[164:167], v186
	ds_read_b128 v[168:171], v186 offset:1024
	ds_read_b128 v[172:175], v186 offset:2048
	ds_read_b128 v[176:179], v186 offset:3072
	ds_read_b128 v[190:193], v186 offset:4096
	ds_read_b128 v[194:197], v186 offset:5120
	ds_read_b128 v[198:201], v186 offset:6144
	ds_read_b128 v[202:205], v186 offset:7168
	global_load_lds_dwordx4 v[150:151], off
	s_mov_b32 m0, s46
	v_lshl_add_u64 v[150:151], v[130:131], 0, s[24:25]
	global_load_lds_dwordx4 v[150:151], off
	s_waitcnt lgkmcnt(8)
	s_barrier
	s_waitcnt lgkmcnt(0)
	s_setprio 1
	v_mfma_f32_16x16x32_bf16 v[116:119], v[134:137], v[164:167], v[116:119]
	s_add_i32 s26, s24, 0xfff50080
	v_mfma_f32_16x16x32_bf16 v[112:115], v[142:145], v[164:167], v[112:115]
	s_cmp_eq_u32 s58, 40
	v_mfma_f32_16x16x32_bf16 v[108:111], v[134:137], v[172:175], v[108:111]
	s_cselect_b32 s59, s19, s21
	v_mfma_f32_16x16x32_bf16 v[104:107], v[142:145], v[172:175], v[104:107]
	s_cselect_b32 s60, s18, s20
	v_mfma_f32_16x16x32_bf16 v[92:95], v[134:137], v[190:193], v[92:95]
	s_cselect_b32 s27, s7, s23
	v_mfma_f32_16x16x32_bf16 v[88:91], v[142:145], v[190:193], v[88:91]
	s_cselect_b32 s61, s6, s22
	v_mfma_f32_16x16x32_bf16 v[76:79], v[134:137], v[198:201], v[76:79]
	v_mfma_f32_16x16x32_bf16 v[72:75], v[142:145], v[198:201], v[72:75]
	v_mfma_f32_16x16x32_bf16 v[116:119], v[138:141], v[168:171], v[116:119]
	v_mfma_f32_16x16x32_bf16 v[112:115], v[146:149], v[168:171], v[112:115]
	v_mfma_f32_16x16x32_bf16 v[108:111], v[138:141], v[176:179], v[108:111]
	v_mfma_f32_16x16x32_bf16 v[104:107], v[146:149], v[176:179], v[104:107]
	v_mfma_f32_16x16x32_bf16 v[92:95], v[138:141], v[194:197], v[92:95]
	v_mfma_f32_16x16x32_bf16 v[88:91], v[146:149], v[194:197], v[88:91]
	v_mfma_f32_16x16x32_bf16 v[76:79], v[138:141], v[202:205], v[76:79]
	v_mfma_f32_16x16x32_bf16 v[72:75], v[146:149], v[202:205], v[72:75]
	s_setprio 0
	s_barrier
	s_cselect_b32 s62, 0, s26
	s_add_u32 s26, s61, s62
	s_addc_u32 s27, s27, 0
	s_mov_b32 m0, s47
	v_lshl_add_u64 v[150:151], s[26:27], 0, v[154:155]
	ds_read_b128 v[206:209], v187
	ds_read_b128 v[210:213], v187 offset:1024
	ds_read_b128 v[214:217], v187 offset:2048
	ds_read_b128 v[222:225], v187 offset:3072
	global_load_lds_dwordx4 v[150:151], off
	s_mov_b32 m0, s48
	v_lshl_add_u64 v[180:181], s[26:27], 0, v[158:159]
	global_load_lds_dwordx4 v[180:181], off
	s_barrier
	s_waitcnt lgkmcnt(0)
	s_setprio 1
	v_mfma_f32_16x16x32_bf16 v[124:127], v[206:209], v[164:167], v[124:127]
	v_mfma_f32_16x16x32_bf16 v[120:123], v[214:217], v[164:167], v[120:123]
	v_mfma_f32_16x16x32_bf16 v[100:103], v[206:209], v[172:175], v[100:103]
	v_mfma_f32_16x16x32_bf16 v[96:99], v[214:217], v[172:175], v[96:99]
	v_mfma_f32_16x16x32_bf16 v[84:87], v[206:209], v[190:193], v[84:87]
	v_mfma_f32_16x16x32_bf16 v[80:83], v[214:217], v[190:193], v[80:83]
	v_mfma_f32_16x16x32_bf16 v[68:71], v[206:209], v[198:201], v[68:71]
	v_mfma_f32_16x16x32_bf16 v[64:67], v[214:217], v[198:201], v[64:67]
	v_mfma_f32_16x16x32_bf16 v[124:127], v[210:213], v[168:171], v[124:127]
	v_mfma_f32_16x16x32_bf16 v[120:123], v[222:225], v[168:171], v[120:123]
	v_mfma_f32_16x16x32_bf16 v[100:103], v[210:213], v[176:179], v[100:103]
	v_mfma_f32_16x16x32_bf16 v[96:99], v[222:225], v[176:179], v[96:99]
	v_mfma_f32_16x16x32_bf16 v[84:87], v[210:213], v[194:197], v[84:87]
	v_mfma_f32_16x16x32_bf16 v[80:83], v[222:225], v[194:197], v[80:83]
	v_mfma_f32_16x16x32_bf16 v[68:71], v[210:213], v[202:205], v[68:71]
	v_mfma_f32_16x16x32_bf16 v[64:67], v[222:225], v[202:205], v[64:67]
	s_setprio 0
	s_add_u32 s60, s60, s62
	s_addc_u32 s61, s59, 0
	s_mov_b32 m0, s37
	v_lshl_add_u64 v[218:219], s[60:61], 0, v[152:153]
	s_barrier
	ds_read_b128 v[164:167], v186 offset:16384
	ds_read_b128 v[168:171], v186 offset:17408
	ds_read_b128 v[172:175], v186 offset:18432
	ds_read_b128 v[176:179], v186 offset:19456
	ds_read_b128 v[190:193], v186 offset:20480
	ds_read_b128 v[194:197], v186 offset:21504
	ds_read_b128 v[198:201], v186 offset:22528
	ds_read_b128 v[202:205], v186 offset:23552
	global_load_lds_dwordx4 v[218:219], off
	s_mov_b32 m0, s38
	v_lshl_add_u64 v[226:227], s[60:61], 0, v[156:157]
	global_load_lds_dwordx4 v[226:227], off
	s_barrier
	s_waitcnt lgkmcnt(0)
	s_setprio 1
	v_mfma_f32_16x16x32_bf16 v[52:55], v[134:137], v[164:167], v[52:55]
	v_mfma_f32_16x16x32_bf16 v[48:51], v[142:145], v[164:167], v[48:51]
	v_mfma_f32_16x16x32_bf16 v[44:47], v[134:137], v[172:175], v[44:47]
	v_mfma_f32_16x16x32_bf16 v[36:39], v[142:145], v[172:175], v[36:39]
	v_mfma_f32_16x16x32_bf16 v[28:31], v[134:137], v[190:193], v[28:31]
	v_mfma_f32_16x16x32_bf16 v[20:23], v[142:145], v[190:193], v[20:23]
	v_mfma_f32_16x16x32_bf16 v[12:15], v[134:137], v[198:201], v[12:15]
	v_mfma_f32_16x16x32_bf16 v[4:7], v[142:145], v[198:201], v[4:7]
	v_mfma_f32_16x16x32_bf16 v[52:55], v[138:141], v[168:171], v[52:55]
	v_mfma_f32_16x16x32_bf16 v[48:51], v[146:149], v[168:171], v[48:51]
	v_mfma_f32_16x16x32_bf16 v[44:47], v[138:141], v[176:179], v[44:47]
	v_mfma_f32_16x16x32_bf16 v[36:39], v[146:149], v[176:179], v[36:39]
	v_mfma_f32_16x16x32_bf16 v[28:31], v[138:141], v[194:197], v[28:31]
	v_mfma_f32_16x16x32_bf16 v[20:23], v[146:149], v[194:197], v[20:23]
	v_mfma_f32_16x16x32_bf16 v[12:15], v[138:141], v[202:205], v[12:15]
	v_mfma_f32_16x16x32_bf16 v[4:7], v[146:149], v[202:205], v[4:7]
	s_setprio 0
	s_barrier
	s_add_u32 s62, s26, 0xb0000
	s_addc_u32 s63, s27, 0
	s_mov_b32 m0, s52
	v_lshl_add_u64 v[134:135], s[62:63], 0, v[154:155]
	global_load_lds_dwordx4 v[134:135], off
	s_mov_b32 m0, s53
	v_lshl_add_u64 v[134:135], s[62:63], 0, v[158:159]
	global_load_lds_dwordx4 v[134:135], off
	s_waitcnt vmcnt(6)
	s_barrier
	s_setprio 1
	v_mfma_f32_16x16x32_bf16 v[60:63], v[206:209], v[164:167], v[60:63]
	v_mfma_f32_16x16x32_bf16 v[56:59], v[214:217], v[164:167], v[56:59]
	v_mfma_f32_16x16x32_bf16 v[40:43], v[206:209], v[172:175], v[40:43]
	v_mfma_f32_16x16x32_bf16 v[32:35], v[214:217], v[172:175], v[32:35]
	v_mfma_f32_16x16x32_bf16 v[24:27], v[206:209], v[190:193], v[24:27]
	v_mfma_f32_16x16x32_bf16 v[16:19], v[214:217], v[190:193], v[16:19]
	v_mfma_f32_16x16x32_bf16 v[8:11], v[206:209], v[198:201], v[8:11]
	v_mfma_f32_16x16x32_bf16 v[0:3], v[214:217], v[198:201], v[0:3]
	v_mfma_f32_16x16x32_bf16 v[60:63], v[210:213], v[168:171], v[60:63]
	v_mfma_f32_16x16x32_bf16 v[56:59], v[222:225], v[168:171], v[56:59]
	v_mfma_f32_16x16x32_bf16 v[40:43], v[210:213], v[176:179], v[40:43]
	v_mfma_f32_16x16x32_bf16 v[32:35], v[222:225], v[176:179], v[32:35]
	v_mfma_f32_16x16x32_bf16 v[24:27], v[210:213], v[194:197], v[24:27]
	v_mfma_f32_16x16x32_bf16 v[16:19], v[222:225], v[194:197], v[16:19]
	v_mfma_f32_16x16x32_bf16 v[8:11], v[210:213], v[202:205], v[8:11]
	v_mfma_f32_16x16x32_bf16 v[0:3], v[222:225], v[202:205], v[0:3]
	s_setprio 0
	s_barrier
	ds_read_b128 v[134:137], v132
	ds_read_b128 v[138:141], v132 offset:1024
	ds_read_b128 v[142:145], v132 offset:2048
	ds_read_b128 v[146:149], v132 offset:3072
	s_add_u32 s60, s60, 0xb0000
	s_addc_u32 s61, s61, 0
	s_mov_b32 m0, s39
	v_lshl_add_u64 v[206:207], s[60:61], 0, v[152:153]
	ds_read_b128 v[164:167], v186 offset:32768
	ds_read_b128 v[168:171], v186 offset:33792
	ds_read_b128 v[172:175], v186 offset:34816
	ds_read_b128 v[176:179], v186 offset:35840
	ds_read_b128 v[190:193], v186 offset:36864
	ds_read_b128 v[194:197], v186 offset:37888
	ds_read_b128 v[198:201], v186 offset:38912
	ds_read_b128 v[202:205], v186 offset:39936
	global_load_lds_dwordx4 v[206:207], off
	s_mov_b32 m0, s40
	v_lshl_add_u64 v[206:207], s[60:61], 0, v[156:157]
	global_load_lds_dwordx4 v[206:207], off
	s_waitcnt lgkmcnt(8)
	s_barrier
	s_waitcnt lgkmcnt(0)
	s_setprio 1
	v_mfma_f32_16x16x32_bf16 v[116:119], v[134:137], v[164:167], v[116:119]
	v_mfma_f32_16x16x32_bf16 v[112:115], v[142:145], v[164:167], v[112:115]
	v_mfma_f32_16x16x32_bf16 v[108:111], v[134:137], v[172:175], v[108:111]
	v_mfma_f32_16x16x32_bf16 v[104:107], v[142:145], v[172:175], v[104:107]
	v_mfma_f32_16x16x32_bf16 v[92:95], v[134:137], v[190:193], v[92:95]
	v_mfma_f32_16x16x32_bf16 v[88:91], v[142:145], v[190:193], v[88:91]
	v_mfma_f32_16x16x32_bf16 v[76:79], v[134:137], v[198:201], v[76:79]
	v_mfma_f32_16x16x32_bf16 v[72:75], v[142:145], v[198:201], v[72:75]
	v_mfma_f32_16x16x32_bf16 v[116:119], v[138:141], v[168:171], v[116:119]
	v_mfma_f32_16x16x32_bf16 v[112:115], v[146:149], v[168:171], v[112:115]
	v_mfma_f32_16x16x32_bf16 v[108:111], v[138:141], v[176:179], v[108:111]
	v_mfma_f32_16x16x32_bf16 v[104:107], v[146:149], v[176:179], v[104:107]
	v_mfma_f32_16x16x32_bf16 v[92:95], v[138:141], v[194:197], v[92:95]
	v_mfma_f32_16x16x32_bf16 v[88:91], v[146:149], v[194:197], v[88:91]
	v_mfma_f32_16x16x32_bf16 v[76:79], v[138:141], v[202:205], v[76:79]
	v_mfma_f32_16x16x32_bf16 v[72:75], v[146:149], v[202:205], v[72:75]
	s_setprio 0
	s_barrier
	s_mov_b32 m0, s54
	v_lshl_add_u64 v[150:151], v[150:151], 0, s[10:11]
	ds_read_b128 v[206:209], v133
	ds_read_b128 v[210:213], v133 offset:1024
	ds_read_b128 v[214:217], v133 offset:2048
	ds_read_b128 v[222:225], v133 offset:3072
	global_load_lds_dwordx4 v[150:151], off
	s_mov_b32 m0, s55
	v_lshl_add_u64 v[150:151], v[180:181], 0, s[10:11]
	global_load_lds_dwordx4 v[150:151], off
	s_barrier
	s_waitcnt lgkmcnt(0)
	s_setprio 1
	v_mfma_f32_16x16x32_bf16 v[124:127], v[206:209], v[164:167], v[124:127]
	v_mfma_f32_16x16x32_bf16 v[120:123], v[214:217], v[164:167], v[120:123]
	v_mfma_f32_16x16x32_bf16 v[100:103], v[206:209], v[172:175], v[100:103]
	v_mfma_f32_16x16x32_bf16 v[96:99], v[214:217], v[172:175], v[96:99]
	v_mfma_f32_16x16x32_bf16 v[84:87], v[206:209], v[190:193], v[84:87]
	v_mfma_f32_16x16x32_bf16 v[80:83], v[214:217], v[190:193], v[80:83]
	v_mfma_f32_16x16x32_bf16 v[68:71], v[206:209], v[198:201], v[68:71]
	v_mfma_f32_16x16x32_bf16 v[64:67], v[214:217], v[198:201], v[64:67]
	v_mfma_f32_16x16x32_bf16 v[124:127], v[210:213], v[168:171], v[124:127]
	v_mfma_f32_16x16x32_bf16 v[120:123], v[222:225], v[168:171], v[120:123]
	v_mfma_f32_16x16x32_bf16 v[100:103], v[210:213], v[176:179], v[100:103]
	v_mfma_f32_16x16x32_bf16 v[96:99], v[222:225], v[176:179], v[96:99]
	v_mfma_f32_16x16x32_bf16 v[84:87], v[210:213], v[194:197], v[84:87]
	v_mfma_f32_16x16x32_bf16 v[80:83], v[222:225], v[194:197], v[80:83]
	v_mfma_f32_16x16x32_bf16 v[68:71], v[210:213], v[202:205], v[68:71]
	v_mfma_f32_16x16x32_bf16 v[64:67], v[222:225], v[202:205], v[64:67]
	s_setprio 0
	s_mov_b32 m0, s42
	v_lshl_add_u64 v[150:151], v[218:219], 0, s[10:11]
	s_barrier
	ds_read_b128 v[164:167], v186 offset:49152
	ds_read_b128 v[168:171], v186 offset:50176
	ds_read_b128 v[172:175], v186 offset:51200
	ds_read_b128 v[176:179], v186 offset:52224
	ds_read_b128 v[190:193], v186 offset:53248
	ds_read_b128 v[194:197], v186 offset:54272
	ds_read_b128 v[198:201], v186 offset:55296
	ds_read_b128 v[202:205], v186 offset:56320
	global_load_lds_dwordx4 v[150:151], off
	s_mov_b32 m0, s43
	v_lshl_add_u64 v[150:151], v[226:227], 0, s[10:11]
	global_load_lds_dwordx4 v[150:151], off
	s_barrier
;     ...
;         G_PAIR(0, 1);
; #pragma unroll 1
;         for (int t = 2; t < nt; t += 2) G_PAIR(t, 0);
	s_waitcnt lgkmcnt(0)
	s_setprio 1
	v_mfma_f32_16x16x32_bf16 v[52:55], v[134:137], v[164:167], v[52:55]
	v_mfma_f32_16x16x32_bf16 v[48:51], v[142:145], v[164:167], v[48:51]
	v_mfma_f32_16x16x32_bf16 v[44:47], v[134:137], v[172:175], v[44:47]
	v_mfma_f32_16x16x32_bf16 v[36:39], v[142:145], v[172:175], v[36:39]
	v_mfma_f32_16x16x32_bf16 v[28:31], v[134:137], v[190:193], v[28:31]
	v_mfma_f32_16x16x32_bf16 v[20:23], v[142:145], v[190:193], v[20:23]
	v_mfma_f32_16x16x32_bf16 v[12:15], v[134:137], v[198:201], v[12:15]
	v_mfma_f32_16x16x32_bf16 v[4:7], v[142:145], v[198:201], v[4:7]
	v_mfma_f32_16x16x32_bf16 v[52:55], v[138:141], v[168:171], v[52:55]
	v_mfma_f32_16x16x32_bf16 v[48:51], v[146:149], v[168:171], v[48:51]
	v_mfma_f32_16x16x32_bf16 v[44:47], v[138:141], v[176:179], v[44:47]
	v_mfma_f32_16x16x32_bf16 v[36:39], v[146:149], v[176:179], v[36:39]
	v_mfma_f32_16x16x32_bf16 v[28:31], v[138:141], v[194:197], v[28:31]
	v_mfma_f32_16x16x32_bf16 v[20:23], v[146:149], v[194:197], v[20:23]
	v_mfma_f32_16x16x32_bf16 v[12:15], v[138:141], v[202:205], v[12:15]
	v_mfma_f32_16x16x32_bf16 v[4:7], v[146:149], v[202:205], v[4:7]
	s_setprio 0
	s_barrier
	s_add_u32 s26, s26, 0xb0080
	s_addc_u32 s27, s27, 0
	s_mov_b32 m0, s56
	v_lshl_add_u64 v[134:135], s[26:27], 0, v[154:155]
	global_load_lds_dwordx4 v[134:135], off
	s_mov_b32 m0, s57
	v_lshl_add_u64 v[134:135], s[26:27], 0, v[158:159]
	global_load_lds_dwordx4 v[134:135], off
	s_waitcnt vmcnt(6)
	s_barrier
	s_setprio 1
	v_mfma_f32_16x16x32_bf16 v[60:63], v[206:209], v[164:167], v[60:63]
	v_mfma_f32_16x16x32_bf16 v[56:59], v[214:217], v[164:167], v[56:59]
	v_mfma_f32_16x16x32_bf16 v[40:43], v[206:209], v[172:175], v[40:43]
	v_mfma_f32_16x16x32_bf16 v[32:35], v[214:217], v[172:175], v[32:35]
	v_mfma_f32_16x16x32_bf16 v[24:27], v[206:209], v[190:193], v[24:27]
	v_mfma_f32_16x16x32_bf16 v[16:19], v[214:217], v[190:193], v[16:19]
	v_mfma_f32_16x16x32_bf16 v[8:11], v[206:209], v[198:201], v[8:11]
	v_mfma_f32_16x16x32_bf16 v[0:3], v[214:217], v[198:201], v[0:3]
	v_mfma_f32_16x16x32_bf16 v[60:63], v[210:213], v[168:171], v[60:63]
	v_mfma_f32_16x16x32_bf16 v[56:59], v[222:225], v[168:171], v[56:59]
	v_mfma_f32_16x16x32_bf16 v[40:43], v[210:213], v[176:179], v[40:43]
	v_mfma_f32_16x16x32_bf16 v[32:35], v[222:225], v[176:179], v[32:35]
	v_mfma_f32_16x16x32_bf16 v[24:27], v[210:213], v[194:197], v[24:27]
	v_mfma_f32_16x16x32_bf16 v[16:19], v[222:225], v[194:197], v[16:19]
	v_mfma_f32_16x16x32_bf16 v[8:11], v[210:213], v[202:205], v[8:11]
	v_mfma_f32_16x16x32_bf16 v[0:3], v[222:225], v[202:205], v[0:3]
	s_setprio 0
	s_add_i32 s58, s58, 2
	s_add_u32 s24, s24, 0x100
	s_addc_u32 s25, s25, 0
	s_cmp_gt_u32 s58, 39
	s_barrier
	s_cbranch_scc0 .LBB0_1906
	ds_read_b128 v[134:137], v185
	ds_read_b128 v[138:141], v185 offset:1024
	ds_read_b128 v[142:145], v185 offset:2048
	ds_read_b128 v[146:149], v185 offset:3072
	s_mov_b32 m0, s45
	v_lshl_add_u64 v[150:151], v[128:129], 0, s[24:25]
	ds_read_b128 v[164:167], v186
	ds_read_b128 v[168:171], v186 offset:1024
	ds_read_b128 v[172:175], v186 offset:2048
	ds_read_b128 v[176:179], v186 offset:3072
	ds_read_b128 v[190:193], v186 offset:4096
	ds_read_b128 v[194:197], v186 offset:5120
	ds_read_b128 v[198:201], v186 offset:6144
	ds_read_b128 v[202:205], v186 offset:7168
	global_load_lds_dwordx4 v[150:151], off
	s_mov_b32 m0, s46
	v_lshl_add_u64 v[150:151], v[130:131], 0, s[24:25]
	global_load_lds_dwordx4 v[150:151], off
	s_waitcnt lgkmcnt(8)
	s_barrier
	s_waitcnt lgkmcnt(0)
	s_setprio 1
	v_mfma_f32_16x16x32_bf16 v[116:119], v[134:137], v[164:167], v[116:119]
	s_add_i32 s26, s24, 0xfff50080
	v_mfma_f32_16x16x32_bf16 v[112:115], v[142:145], v[164:167], v[112:115]
	s_cmp_eq_u32 s58, 40
	v_mfma_f32_16x16x32_bf16 v[108:111], v[134:137], v[172:175], v[108:111]
	s_cselect_b32 s59, s19, s21
	v_mfma_f32_16x16x32_bf16 v[104:107], v[142:145], v[172:175], v[104:107]
	s_cselect_b32 s60, s18, s20
	v_mfma_f32_16x16x32_bf16 v[92:95], v[134:137], v[190:193], v[92:95]
	s_cselect_b32 s27, s7, s23
	v_mfma_f32_16x16x32_bf16 v[88:91], v[142:145], v[190:193], v[88:91]
	s_cselect_b32 s61, s6, s22
	v_mfma_f32_16x16x32_bf16 v[76:79], v[134:137], v[198:201], v[76:79]
	v_mfma_f32_16x16x32_bf16 v[72:75], v[142:145], v[198:201], v[72:75]
	v_mfma_f32_16x16x32_bf16 v[116:119], v[138:141], v[168:171], v[116:119]
	v_mfma_f32_16x16x32_bf16 v[112:115], v[146:149], v[168:171], v[112:115]
	v_mfma_f32_16x16x32_bf16 v[108:111], v[138:141], v[176:179], v[108:111]
	v_mfma_f32_16x16x32_bf16 v[104:107], v[146:149], v[176:179], v[104:107]
	v_mfma_f32_16x16x32_bf16 v[92:95], v[138:141], v[194:197], v[92:95]
	v_mfma_f32_16x16x32_bf16 v[88:91], v[146:149], v[194:197], v[88:91]
	v_mfma_f32_16x16x32_bf16 v[76:79], v[138:141], v[202:205], v[76:79]
	v_mfma_f32_16x16x32_bf16 v[72:75], v[146:149], v[202:205], v[72:75]
	s_setprio 0
	s_barrier
	s_cselect_b32 s62, 0, s26
	s_add_u32 s26, s61, s62
	s_addc_u32 s27, s27, 0
	s_mov_b32 m0, s47
	v_lshl_add_u64 v[150:151], s[26:27], 0, v[154:155]
	ds_read_b128 v[206:209], v187
	ds_read_b128 v[210:213], v187 offset:1024
	ds_read_b128 v[214:217], v187 offset:2048
	ds_read_b128 v[222:225], v187 offset:3072
	global_load_lds_dwordx4 v[150:151], off
	s_mov_b32 m0, s48
	v_lshl_add_u64 v[180:181], s[26:27], 0, v[158:159]
	global_load_lds_dwordx4 v[180:181], off
	s_barrier
;     __device__ __forceinline__ void epi(const f32x4 (&acc)[2][2][4][2], const Unit& u, int wr, int wc, int fr, int fq) const {
;     ...
;                 for (int bj = 0; bj < 2; ++bj) xo[m][bj] = *(const u32x4*)(xb + (size_t)(row0 + ai * 128 + m * 16) * D + col0 + bj * 128);
	s_waitcnt lgkmcnt(0)
	s_setprio 1
	v_mfma_f32_16x16x32_bf16 v[124:127], v[206:209], v[164:167], v[124:127]
	v_mfma_f32_16x16x32_bf16 v[120:123], v[214:217], v[164:167], v[120:123]
	v_mfma_f32_16x16x32_bf16 v[100:103], v[206:209], v[172:175], v[100:103]
	v_mfma_f32_16x16x32_bf16 v[96:99], v[214:217], v[172:175], v[96:99]
	v_mfma_f32_16x16x32_bf16 v[84:87], v[206:209], v[190:193], v[84:87]
	v_mfma_f32_16x16x32_bf16 v[80:83], v[214:217], v[190:193], v[80:83]
	v_mfma_f32_16x16x32_bf16 v[68:71], v[206:209], v[198:201], v[68:71]
	v_mfma_f32_16x16x32_bf16 v[64:67], v[214:217], v[198:201], v[64:67]
	v_mfma_f32_16x16x32_bf16 v[124:127], v[210:213], v[168:171], v[124:127]
	v_mfma_f32_16x16x32_bf16 v[120:123], v[222:225], v[168:171], v[120:123]
	v_mfma_f32_16x16x32_bf16 v[100:103], v[210:213], v[176:179], v[100:103]
	v_mfma_f32_16x16x32_bf16 v[96:99], v[222:225], v[176:179], v[96:99]
	v_mfma_f32_16x16x32_bf16 v[84:87], v[210:213], v[194:197], v[84:87]
	v_mfma_f32_16x16x32_bf16 v[80:83], v[222:225], v[194:197], v[80:83]
	v_mfma_f32_16x16x32_bf16 v[68:71], v[210:213], v[202:205], v[68:71]
	v_mfma_f32_16x16x32_bf16 v[64:67], v[222:225], v[202:205], v[64:67]
	s_setprio 0
	s_add_u32 s60, s60, s62
	s_addc_u32 s61, s59, 0
	s_mov_b32 m0, s37
	v_lshl_add_u64 v[218:219], s[60:61], 0, v[152:153]
	s_barrier
	ds_read_b128 v[164:167], v186 offset:16384
	ds_read_b128 v[168:171], v186 offset:17408
	ds_read_b128 v[172:175], v186 offset:18432
	ds_read_b128 v[176:179], v186 offset:19456
	ds_read_b128 v[190:193], v186 offset:20480
	ds_read_b128 v[194:197], v186 offset:21504
	ds_read_b128 v[198:201], v186 offset:22528
	ds_read_b128 v[202:205], v186 offset:23552
	global_load_lds_dwordx4 v[218:219], off
	s_mov_b32 m0, s38
	v_lshl_add_u64 v[226:227], s[60:61], 0, v[156:157]
	global_load_lds_dwordx4 v[226:227], off
	s_barrier
	s_waitcnt lgkmcnt(0)
	s_setprio 1
	v_mfma_f32_16x16x32_bf16 v[52:55], v[134:137], v[164:167], v[52:55]
	v_mfma_f32_16x16x32_bf16 v[48:51], v[142:145], v[164:167], v[48:51]
	v_mfma_f32_16x16x32_bf16 v[44:47], v[134:137], v[172:175], v[44:47]
	v_mfma_f32_16x16x32_bf16 v[36:39], v[142:145], v[172:175], v[36:39]
	v_mfma_f32_16x16x32_bf16 v[28:31], v[134:137], v[190:193], v[28:31]
	v_mfma_f32_16x16x32_bf16 v[20:23], v[142:145], v[190:193], v[20:23]
	v_mfma_f32_16x16x32_bf16 v[12:15], v[134:137], v[198:201], v[12:15]
	v_mfma_f32_16x16x32_bf16 v[4:7], v[142:145], v[198:201], v[4:7]
	v_mfma_f32_16x16x32_bf16 v[52:55], v[138:141], v[168:171], v[52:55]
	v_mfma_f32_16x16x32_bf16 v[48:51], v[146:149], v[168:171], v[48:51]
	v_mfma_f32_16x16x32_bf16 v[44:47], v[138:141], v[176:179], v[44:47]
	v_mfma_f32_16x16x32_bf16 v[36:39], v[146:149], v[176:179], v[36:39]
	v_mfma_f32_16x16x32_bf16 v[28:31], v[138:141], v[194:197], v[28:31]
	v_mfma_f32_16x16x32_bf16 v[20:23], v[146:149], v[194:197], v[20:23]
	v_mfma_f32_16x16x32_bf16 v[12:15], v[138:141], v[202:205], v[12:15]
	v_mfma_f32_16x16x32_bf16 v[4:7], v[146:149], v[202:205], v[4:7]
	s_setprio 0
	s_barrier
	s_add_u32 s62, s26, 0xb0000
	s_addc_u32 s63, s27, 0
	s_mov_b32 m0, s52
	v_lshl_add_u64 v[134:135], s[62:63], 0, v[154:155]
	global_load_lds_dwordx4 v[134:135], off
	s_mov_b32 m0, s53
	v_lshl_add_u64 v[134:135], s[62:63], 0, v[158:159]
	global_load_lds_dwordx4 v[134:135], off
	s_waitcnt vmcnt(6)
	s_barrier
	s_setprio 1
	v_mfma_f32_16x16x32_bf16 v[60:63], v[206:209], v[164:167], v[60:63]
	v_lshl_or_b32 v248, s30, 8, v184
	v_mfma_f32_16x16x32_bf16 v[56:59], v[214:217], v[164:167], v[56:59]
	v_lshl_add_u32 v250, s2, 8, v182
	v_mfma_f32_16x16x32_bf16 v[40:43], v[206:209], v[172:175], v[40:43]
	v_ashrrev_i32_e32 v249, 31, v248
	v_mfma_f32_16x16x32_bf16 v[32:35], v[214:217], v[172:175], v[32:35]
	v_lshlrev_b64 v[248:249], 1, v[248:249]
	v_mfma_f32_16x16x32_bf16 v[24:27], v[206:209], v[190:193], v[24:27]
	v_ashrrev_i32_e32 v251, 31, v250
	v_mfma_f32_16x16x32_bf16 v[16:19], v[214:217], v[190:193], v[16:19]
	v_lshl_add_u64 v[248:249], s[0:1], 0, v[248:249]
	v_mfma_f32_16x16x32_bf16 v[8:11], v[206:209], v[198:201], v[8:11]
	v_lshlrev_b64 v[250:251], 11, v[250:251]
	v_mfma_f32_16x16x32_bf16 v[0:3], v[214:217], v[198:201], v[0:3]
	v_lshl_add_u64 v[252:253], v[248:249], 0, v[250:251]
	v_mfma_f32_16x16x32_bf16 v[60:63], v[210:213], v[168:171], v[60:63]
	global_load_dwordx4 v[232:235], v[252:253], off
	v_mfma_f32_16x16x32_bf16 v[56:59], v[222:225], v[168:171], v[56:59]
	global_load_dwordx4 v[236:239], v[252:253], off offset:256
	v_mfma_f32_16x16x32_bf16 v[40:43], v[210:213], v[176:179], v[40:43]
	v_mov_b32_e32 v250, 0x8000
	v_mfma_f32_16x16x32_bf16 v[32:35], v[222:225], v[176:179], v[32:35]
	v_mov_b32_e32 v251, 0
	v_mfma_f32_16x16x32_bf16 v[24:27], v[210:213], v[194:197], v[24:27]
	v_lshl_add_u64 v[250:251], v[252:253], 0, v[250:251]
	v_mfma_f32_16x16x32_bf16 v[16:19], v[222:225], v[194:197], v[16:19]
	global_load_dwordx4 v[240:243], v[250:251], off
	v_mfma_f32_16x16x32_bf16 v[8:11], v[210:213], v[202:205], v[8:11]
	global_load_dwordx4 v[244:247], v[250:251], off offset:256
	v_mfma_f32_16x16x32_bf16 v[0:3], v[222:225], v[202:205], v[0:3]
	s_setprio 0
	s_barrier
	ds_read_b128 v[134:137], v132
	ds_read_b128 v[138:141], v132 offset:1024
	ds_read_b128 v[142:145], v132 offset:2048
	ds_read_b128 v[146:149], v132 offset:3072
	s_add_u32 s60, s60, 0xb0000
	s_addc_u32 s61, s61, 0
	s_mov_b32 m0, s39
	v_lshl_add_u64 v[206:207], s[60:61], 0, v[152:153]
	ds_read_b128 v[164:167], v186 offset:32768
	ds_read_b128 v[168:171], v186 offset:33792
	ds_read_b128 v[172:175], v186 offset:34816
	ds_read_b128 v[176:179], v186 offset:35840
	ds_read_b128 v[190:193], v186 offset:36864
	ds_read_b128 v[194:197], v186 offset:37888
	ds_read_b128 v[198:201], v186 offset:38912
	ds_read_b128 v[202:205], v186 offset:39936
	global_load_lds_dwordx4 v[206:207], off
	s_mov_b32 m0, s40
	v_lshl_add_u64 v[206:207], s[60:61], 0, v[156:157]
	global_load_lds_dwordx4 v[206:207], off
	s_waitcnt lgkmcnt(8)
	s_barrier
	s_waitcnt lgkmcnt(0)
	s_setprio 1
	v_mfma_f32_16x16x32_bf16 v[116:119], v[134:137], v[164:167], v[116:119]
	v_mfma_f32_16x16x32_bf16 v[112:115], v[142:145], v[164:167], v[112:115]
	v_mfma_f32_16x16x32_bf16 v[108:111], v[134:137], v[172:175], v[108:111]
	v_mfma_f32_16x16x32_bf16 v[104:107], v[142:145], v[172:175], v[104:107]
	v_mfma_f32_16x16x32_bf16 v[92:95], v[134:137], v[190:193], v[92:95]
	v_mfma_f32_16x16x32_bf16 v[88:91], v[142:145], v[190:193], v[88:91]
	v_mfma_f32_16x16x32_bf16 v[76:79], v[134:137], v[198:201], v[76:79]
	v_mfma_f32_16x16x32_bf16 v[72:75], v[142:145], v[198:201], v[72:75]
	v_mfma_f32_16x16x32_bf16 v[116:119], v[138:141], v[168:171], v[116:119]
	v_mfma_f32_16x16x32_bf16 v[112:115], v[146:149], v[168:171], v[112:115]
	v_mfma_f32_16x16x32_bf16 v[108:111], v[138:141], v[176:179], v[108:111]
	v_mfma_f32_16x16x32_bf16 v[104:107], v[146:149], v[176:179], v[104:107]
	v_mfma_f32_16x16x32_bf16 v[92:95], v[138:141], v[194:197], v[92:95]
	v_mfma_f32_16x16x32_bf16 v[88:91], v[146:149], v[194:197], v[88:91]
	v_mfma_f32_16x16x32_bf16 v[76:79], v[138:141], v[202:205], v[76:79]
	v_mfma_f32_16x16x32_bf16 v[72:75], v[146:149], v[202:205], v[72:75]
	s_setprio 0
	s_barrier
	s_mov_b32 m0, s54
	v_lshl_add_u64 v[150:151], v[150:151], 0, s[10:11]
	ds_read_b128 v[206:209], v133
	ds_read_b128 v[210:213], v133 offset:1024
	ds_read_b128 v[214:217], v133 offset:2048
	ds_read_b128 v[222:225], v133 offset:3072
	global_load_lds_dwordx4 v[150:151], off
	s_mov_b32 m0, s55
	v_lshl_add_u64 v[150:151], v[180:181], 0, s[10:11]
	global_load_lds_dwordx4 v[150:151], off
	s_barrier
	s_waitcnt lgkmcnt(0)
	s_setprio 1
	v_mfma_f32_16x16x32_bf16 v[124:127], v[206:209], v[164:167], v[124:127]
	v_mfma_f32_16x16x32_bf16 v[120:123], v[214:217], v[164:167], v[120:123]
	v_mfma_f32_16x16x32_bf16 v[100:103], v[206:209], v[172:175], v[100:103]
	v_mfma_f32_16x16x32_bf16 v[96:99], v[214:217], v[172:175], v[96:99]
	v_mfma_f32_16x16x32_bf16 v[84:87], v[206:209], v[190:193], v[84:87]
	v_mfma_f32_16x16x32_bf16 v[80:83], v[214:217], v[190:193], v[80:83]
	v_mfma_f32_16x16x32_bf16 v[68:71], v[206:209], v[198:201], v[68:71]
	v_mfma_f32_16x16x32_bf16 v[64:67], v[214:217], v[198:201], v[64:67]
	v_mfma_f32_16x16x32_bf16 v[124:127], v[210:213], v[168:171], v[124:127]
	v_mfma_f32_16x16x32_bf16 v[120:123], v[222:225], v[168:171], v[120:123]
	v_mfma_f32_16x16x32_bf16 v[100:103], v[210:213], v[176:179], v[100:103]
	v_mfma_f32_16x16x32_bf16 v[96:99], v[222:225], v[176:179], v[96:99]
	v_mfma_f32_16x16x32_bf16 v[84:87], v[210:213], v[194:197], v[84:87]
	v_mfma_f32_16x16x32_bf16 v[80:83], v[222:225], v[194:197], v[80:83]
	v_mfma_f32_16x16x32_bf16 v[68:71], v[210:213], v[202:205], v[68:71]
	v_mfma_f32_16x16x32_bf16 v[64:67], v[222:225], v[202:205], v[64:67]
	s_setprio 0
	s_mov_b32 m0, s42
	v_lshl_add_u64 v[150:151], v[218:219], 0, s[10:11]
	s_barrier
	ds_read_b128 v[164:167], v186 offset:49152
	ds_read_b128 v[168:171], v186 offset:50176
	ds_read_b128 v[172:175], v186 offset:51200
	ds_read_b128 v[176:179], v186 offset:52224
	ds_read_b128 v[190:193], v186 offset:53248
	ds_read_b128 v[194:197], v186 offset:54272
	ds_read_b128 v[198:201], v186 offset:55296
	ds_read_b128 v[202:205], v186 offset:56320
	global_load_lds_dwordx4 v[150:151], off
	s_mov_b32 m0, s43
	v_lshl_add_u64 v[150:151], v[226:227], 0, s[10:11]
	global_load_lds_dwordx4 v[150:151], off
	s_barrier
	s_waitcnt lgkmcnt(0)
	s_setprio 1
	v_mfma_f32_16x16x32_bf16 v[52:55], v[134:137], v[164:167], v[52:55]
	v_mfma_f32_16x16x32_bf16 v[48:51], v[142:145], v[164:167], v[48:51]
	v_mfma_f32_16x16x32_bf16 v[44:47], v[134:137], v[172:175], v[44:47]
	v_mfma_f32_16x16x32_bf16 v[36:39], v[142:145], v[172:175], v[36:39]
	v_mfma_f32_16x16x32_bf16 v[28:31], v[134:137], v[190:193], v[28:31]
	v_mfma_f32_16x16x32_bf16 v[20:23], v[142:145], v[190:193], v[20:23]
	v_mfma_f32_16x16x32_bf16 v[12:15], v[134:137], v[198:201], v[12:15]
	v_mfma_f32_16x16x32_bf16 v[4:7], v[142:145], v[198:201], v[4:7]
	v_mfma_f32_16x16x32_bf16 v[52:55], v[138:141], v[168:171], v[52:55]
	v_mfma_f32_16x16x32_bf16 v[48:51], v[146:149], v[168:171], v[48:51]
	v_mfma_f32_16x16x32_bf16 v[44:47], v[138:141], v[176:179], v[44:47]
	v_mfma_f32_16x16x32_bf16 v[36:39], v[146:149], v[176:179], v[36:39]
	v_mfma_f32_16x16x32_bf16 v[28:31], v[138:141], v[194:197], v[28:31]
	v_mfma_f32_16x16x32_bf16 v[20:23], v[146:149], v[194:197], v[20:23]
	v_mfma_f32_16x16x32_bf16 v[12:15], v[138:141], v[202:205], v[12:15]
	v_mfma_f32_16x16x32_bf16 v[4:7], v[146:149], v[202:205], v[4:7]
	s_setprio 0
	s_barrier
	s_add_u32 s26, s26, 0xb0080
	s_addc_u32 s27, s27, 0
	s_mov_b32 m0, s56
	v_lshl_add_u64 v[134:135], s[26:27], 0, v[154:155]
	global_load_lds_dwordx4 v[134:135], off
	s_mov_b32 m0, s57
	v_lshl_add_u64 v[134:135], s[26:27], 0, v[158:159]
	global_load_lds_dwordx4 v[134:135], off
	s_waitcnt vmcnt(6)
	s_barrier
	s_setprio 1
	v_mfma_f32_16x16x32_bf16 v[60:63], v[206:209], v[164:167], v[60:63]
	v_mfma_f32_16x16x32_bf16 v[56:59], v[214:217], v[164:167], v[56:59]
	v_mfma_f32_16x16x32_bf16 v[40:43], v[206:209], v[172:175], v[40:43]
	v_mfma_f32_16x16x32_bf16 v[32:35], v[214:217], v[172:175], v[32:35]
	v_mfma_f32_16x16x32_bf16 v[24:27], v[206:209], v[190:193], v[24:27]
	v_mfma_f32_16x16x32_bf16 v[16:19], v[214:217], v[190:193], v[16:19]
	v_mfma_f32_16x16x32_bf16 v[8:11], v[206:209], v[198:201], v[8:11]
	v_mfma_f32_16x16x32_bf16 v[0:3], v[214:217], v[198:201], v[0:3]
	v_mfma_f32_16x16x32_bf16 v[60:63], v[210:213], v[168:171], v[60:63]
	v_mfma_f32_16x16x32_bf16 v[56:59], v[222:225], v[168:171], v[56:59]
	v_mfma_f32_16x16x32_bf16 v[40:43], v[210:213], v[176:179], v[40:43]
	v_mfma_f32_16x16x32_bf16 v[32:35], v[222:225], v[176:179], v[32:35]
	v_mfma_f32_16x16x32_bf16 v[24:27], v[210:213], v[194:197], v[24:27]
	v_mfma_f32_16x16x32_bf16 v[16:19], v[222:225], v[194:197], v[16:19]
	v_mfma_f32_16x16x32_bf16 v[8:11], v[210:213], v[202:205], v[8:11]
	v_mfma_f32_16x16x32_bf16 v[0:3], v[222:225], v[202:205], v[0:3]
	s_setprio 0
	s_add_i32 s58, s58, 2
	s_add_u32 s24, s24, 0x100
	s_addc_u32 s25, s25, 0
	s_cmp_gt_u32 s58, 41
	s_barrier
; __device__ __forceinline__ unsigned pk2(float lo, float hi) { unsigned r; asm volatile("v_cvt_pk_bf16_f32 %0, %1, %2" : "=v"(r) : "v"(lo), "v"(hi)); return r; }
; __device__ __forceinline__ unsigned pk2(float lo, float hi) { return f2bf(lo) | (f2bf(hi) << 16); }
;     __device__ __forceinline__ void epi(const f32x4 (&acc)[2][2][4][2], const Unit& u, int wr, int wc, int fr, int fq) const {
;     ...
;         for (int ai = 0; ai < 2; ++ai) {
;             u32x4 xo[4][2];
; #pragma unroll
;             for (int m = 0; m < 4; ++m)
; #pragma unroll
;                 for (int bj = 0; bj < 2; ++bj) xo[m][bj] = *(const u32x4*)(xb + (size_t)(row0 + ai * 128 + m * 16) * D + col0 + bj * 128);
; #pragma unroll
;             for (int m = 0; m < 4; ++m) {
;                 const int row = row0 + ai * 128 + m * 16; const size_t off = (size_t)row * D + col0; float ss = 0.f;
; #pragma unroll
;                 for (int bj = 0; bj < 2; ++bj) {
;                     const u32x4 o = xo[m][bj]; const f32x4 a0v = acc[ai][bj][m][0], a1v = acc[ai][bj][m][1];
;                     const float v0 = bf_lo(o.x) + coef * a0v[0], v1 = bf_hi(o.x) + coef * a0v[1], v2 = bf_lo(o.y) + coef * a0v[2], v3 = bf_hi(o.y) + coef * a0v[3];
;                     const float v4 = bf_lo(o.z) + coef * a1v[0], v5 = bf_hi(o.z) + coef * a1v[1], v6 = bf_lo(o.w) + coef * a1v[2], v7 = bf_hi(o.w) + coef * a1v[3];
;                     u32x4 w; w.x = pk2(v0, v1); w.y = pk2(v2, v3); w.z = pk2(v4, v5); w.w = pk2(v6, v7);
;                     *(u32x4*)(xb + off + bj * 128) = w;
;                     ss += ((v0 * v0 + v1 * v1) + (v2 * v2 + v3 * v3)) + ((v4 * v4 + v5 * v5) + (v6 * v6 + v7 * v7));
;                 }
;                 ss += __shfl_xor(ss, 16); ss += __shfl_xor(ss, 32);
;                 if (fq == 0) rowss[(size_t)row * 32 + u.pn * 4 + wc] = ss;
	v_lshl_or_b32 v164, s30, 8, v184
	v_lshl_add_u32 v168, s2, 8, v182
	v_ashrrev_i32_e32 v165, 31, v164
	v_lshlrev_b64 v[198:199], 1, v[164:165]
	v_ashrrev_i32_e32 v169, 31, v168
	v_lshl_add_u64 v[166:167], s[0:1], 0, v[198:199]
	v_lshlrev_b64 v[200:201], 11, v[168:169]
	v_lshl_add_u64 v[128:129], v[166:167], 0, v[200:201]
	v_mov_b32_e32 v218, 0x40000
	v_mov_b32_e32 v219, 0
	v_lshl_add_u64 v[216:217], v[128:129], 0, v[218:219]
	v_mov_b32_e32 v218, 0x8000
	s_waitcnt vmcnt(8)
	v_mov_b64_e32 v[190:191], v[232:233]
	v_mov_b64_e32 v[192:193], v[234:235]
	v_mov_b64_e32 v[194:195], v[236:237]
	v_mov_b64_e32 v[196:197], v[238:239]
	v_or_b32_e32 v178, 16, v168
	v_or_b32_e32 v174, 32, v168
	v_or_b32_e32 v170, 48, v168
	v_ashrrev_i32_e32 v179, 31, v178
	v_ashrrev_i32_e32 v175, 31, v174
	v_ashrrev_i32_e32 v171, 31, v170
	v_lshlrev_b64 v[180:181], 11, v[178:179]
	v_lshlrev_b64 v[176:177], 11, v[174:175]
	v_lshlrev_b64 v[172:173], 11, v[170:171]
	v_lshl_add_u64 v[128:129], v[166:167], 0, v[180:181]
	v_lshl_add_u64 v[130:131], v[166:167], 0, v[176:177]
	v_lshl_add_u64 v[202:203], v[166:167], 0, v[172:173]
	v_mov_b64_e32 v[148:149], v[240:241]
	v_mov_b64_e32 v[150:151], v[242:243]
	v_mov_b64_e32 v[144:145], v[244:245]
	v_mov_b64_e32 v[146:147], v[246:247]
	global_load_dwordx4 v[140:143], v[130:131], off
	global_load_dwordx4 v[136:139], v[130:131], off offset:256
	global_load_dwordx4 v[132:135], v[202:203], off
	s_nop 0
	global_load_dwordx4 v[128:131], v[202:203], off offset:256
	global_load_dwordx4 v[222:225], v[216:217], off
	global_load_dwordx4 v[226:229], v[216:217], off offset:256
	v_lshl_add_u64 v[216:217], v[216:217], 0, v[218:219]
	global_load_dwordx4 v[230:233], v[216:217], off
	global_load_dwordx4 v[234:237], v[216:217], off offset:256
	v_lshl_add_u64 v[216:217], v[216:217], 0, v[218:219]
	global_load_dwordx4 v[238:241], v[216:217], off
	global_load_dwordx4 v[242:245], v[216:217], off offset:256
	v_lshl_add_u64 v[216:217], v[216:217], 0, v[218:219]
	global_load_dwordx4 v[246:249], v[216:217], off
	global_load_dwordx4 v[250:253], v[216:217], off offset:256
	v_and_b32_e32 v202, 64, v188
	v_xor_b32_e32 v189, 16, v188
	v_add_u32_e32 v202, 64, v202
	v_cmp_lt_i32_e32 vcc, v189, v202
	v_lshlrev_b32_e32 v203, 16, v190
	v_and_b32_e32 v190, 0xffff0000, v190
	v_lshlrev_b32_e32 v204, 16, v191
	v_and_b32_e32 v191, 0xffff0000, v191
	v_lshlrev_b32_e32 v205, 16, v192
	v_and_b32_e32 v192, 0xffff0000, v192
	v_lshlrev_b32_e32 v206, 16, v193
	v_and_b32_e32 v193, 0xffff0000, v193
	v_lshlrev_b32_e32 v207, 16, v194
	v_and_b32_e32 v194, 0xffff0000, v194
	v_lshlrev_b32_e32 v208, 16, v195
	v_and_b32_e32 v195, 0xffff0000, v195
	v_lshlrev_b32_e32 v209, 16, v196
	v_and_b32_e32 v196, 0xffff0000, v196
	v_lshlrev_b32_e32 v210, 16, v197
	v_and_b32_e32 v197, 0xffff0000, v197
	v_fmac_f32_e32 v190, 0.5, v117
	v_fmac_f32_e32 v191, 0.5, v119
	v_fmac_f32_e32 v192, 0.5, v113
	v_fmac_f32_e32 v193, 0.5, v115
	v_fmac_f32_e32 v194, 0.5, v125
	v_fmac_f32_e32 v195, 0.5, v127
	v_fmac_f32_e32 v196, 0.5, v121
	v_fmac_f32_e32 v197, 0.5, v123
	v_fmac_f32_e32 v203, 0.5, v116
	v_fmac_f32_e32 v204, 0.5, v118
	v_fmac_f32_e32 v205, 0.5, v112
	v_fmac_f32_e32 v206, 0.5, v114
	v_fmac_f32_e32 v207, 0.5, v124
	v_fmac_f32_e32 v208, 0.5, v126
	v_fmac_f32_e32 v209, 0.5, v120
	v_fmac_f32_e32 v210, 0.5, v122
	v_mul_f32_e32 v112, v190, v190
	v_mul_f32_e32 v113, v191, v191
	v_mul_f32_e32 v118, v192, v192
	v_mul_f32_e32 v119, v193, v193
	v_mul_f32_e32 v120, v194, v194
	v_mul_f32_e32 v121, v195, v195
	v_mul_f32_e32 v122, v196, v196
	v_mul_f32_e32 v123, v197, v197
	v_fmac_f32_e32 v112, v203, v203
	v_fmac_f32_e32 v113, v204, v204
	v_fmac_f32_e32 v118, v205, v205
	v_fmac_f32_e32 v119, v206, v206
	v_fmac_f32_e32 v120, v207, v207
	v_fmac_f32_e32 v121, v208, v208
	v_fmac_f32_e32 v122, v209, v209
	v_fmac_f32_e32 v123, v210, v210
	v_add_f32_e32 v112, v112, v113
	v_add_f32_e32 v113, v118, v119
	v_add_f32_e32 v118, v120, v121
	v_add_f32_e32 v119, v122, v123
	v_cndmask_b32_e32 v189, v188, v189, vcc
	v_add_f32_e32 v112, v112, v113
	v_add_f32_e32 v113, v118, v119
	v_add_f32_e32 v113, v112, v113
	v_lshlrev_b32_e32 v112, 2, v189
	ds_bpermute_b32 v122, v112, v113
	v_lshl_add_u64 v[118:119], s[0:1], 0, v[200:201]
	v_cvt_pk_bf16_f32 v114, v203, v190
	v_lshl_add_u64 v[120:121], v[118:119], 0, v[198:199]
	v_cvt_pk_bf16_f32 v115, v204, v191
	v_cvt_pk_bf16_f32 v116, v205, v192
	v_cvt_pk_bf16_f32 v117, v206, v193
	global_store_dwordx4 v[120:121], v[114:117], off
	s_waitcnt lgkmcnt(0)
	s_nop 0
	v_add_f32_e32 v114, v113, v122
	v_xor_b32_e32 v113, 32, v188
	v_cmp_lt_i32_e32 vcc, v113, v202
	v_cvt_pk_bf16_f32 v116, v207, v194
	v_cvt_pk_bf16_f32 v117, v208, v195
	v_cvt_pk_bf16_f32 v118, v209, v196
	v_cvt_pk_bf16_f32 v119, v210, v197
	global_store_dwordx4 v[120:121], v[116:119], off offset:256
	s_nop 0
	v_cndmask_b32_e32 v113, v188, v113, vcc
	v_lshlrev_b32_e32 v113, 2, v113
	ds_bpermute_b32 v115, v113, v114
	s_and_saveexec_b64 s[20:21], s[4:5]
	s_cbranch_execz .LBB0_1909
	s_waitcnt lgkmcnt(0)
	v_add_f32_e32 v116, v114, v115
	s_lshl_b32 s22, s30, 2
	v_lshlrev_b64 v[114:115], 7, v[168:169]
	s_ashr_i32 s23, s22, 31
	v_lshl_add_u64 v[114:115], s[8:9], 0, v[114:115]
	v_lshl_add_u64 v[114:115], s[22:23], 2, v[114:115]
	s_lshl_b32 s2, s41, 2
	v_lshl_add_u64 v[114:115], v[114:115], 0, s[2:3]
	global_store_dword v[114:115], v116, off

; __device__ __forceinline__ unsigned pk2(float lo, float hi) { unsigned r; asm volatile("v_cvt_pk_bf16_f32 %0, %1, %2" : "=v"(r) : "v"(lo), "v"(hi)); return r; }
; __device__ __forceinline__ unsigned pk2(float lo, float hi) { return f2bf(lo) | (f2bf(hi) << 16); }
;     __device__ __forceinline__ void epi(const f32x4 (&acc)[2][2][4][2], const Unit& u, int wr, int wc, int fr, int fq) const {
;     ...
;             for (int m = 0; m < 4; ++m) {
;                 const int row = row0 + ai * 128 + m * 16; const size_t off = (size_t)row * D + col0; float ss = 0.f;
; #pragma unroll
;                 for (int bj = 0; bj < 2; ++bj) {
;                     const u32x4 o = xo[m][bj]; const f32x4 a0v = acc[ai][bj][m][0], a1v = acc[ai][bj][m][1];
;                     const float v0 = bf_lo(o.x) + coef * a0v[0], v1 = bf_hi(o.x) + coef * a0v[1], v2 = bf_lo(o.y) + coef * a0v[2], v3 = bf_hi(o.y) + coef * a0v[3];
;                     const float v4 = bf_lo(o.z) + coef * a1v[0], v5 = bf_hi(o.z) + coef * a1v[1], v6 = bf_lo(o.w) + coef * a1v[2], v7 = bf_hi(o.w) + coef * a1v[3];
;                     u32x4 w; w.x = pk2(v0, v1); w.y = pk2(v2, v3); w.z = pk2(v4, v5); w.w = pk2(v6, v7);
;                     *(u32x4*)(xb + off + bj * 128) = w;
;                     ss += ((v0 * v0 + v1 * v1) + (v2 * v2 + v3 * v3)) + ((v4 * v4 + v5 * v5) + (v6 * v6 + v7 * v7));
;                 }
;                 ss += __shfl_xor(ss, 16); ss += __shfl_xor(ss, 32);
;                 if (fq == 0) rowss[(size_t)row * 32 + u.pn * 4 + wc] = ss;
.LBB0_1911:
	s_or_b64 exec, exec, s[20:21]
	s_waitcnt vmcnt(12)
	v_lshlrev_b32_e32 v96, 16, v140
	v_fmac_f32_e32 v96, 0.5, v92
	v_and_b32_e32 v92, 0xffff0000, v140
	v_fmac_f32_e32 v92, 0.5, v93
	v_lshlrev_b32_e32 v93, 16, v141
	v_fmac_f32_e32 v93, 0.5, v94
	v_and_b32_e32 v94, 0xffff0000, v141
	v_fmac_f32_e32 v94, 0.5, v95
	v_lshlrev_b32_e32 v95, 16, v142
	s_waitcnt lgkmcnt(0)
	v_and_b32_e32 v97, 0xffff0000, v142
	v_fmac_f32_e32 v95, 0.5, v88
	v_fmac_f32_e32 v97, 0.5, v89
	v_and_b32_e32 v99, 0xffff0000, v143
	v_cvt_pk_bf16_f32 v88, v96, v92
	v_cvt_pk_bf16_f32 v89, v93, v94
	v_mul_f32_e32 v92, v92, v92
	v_mul_f32_e32 v94, v94, v94
	v_lshlrev_b32_e32 v98, 16, v143
	v_fmac_f32_e32 v99, 0.5, v91
	v_fmac_f32_e32 v92, v96, v96
	v_fmac_f32_e32 v94, v93, v93
	v_fmac_f32_e32 v98, 0.5, v90
	v_add_f32_e32 v92, v92, v94
	v_mul_f32_e32 v93, v97, v97
	v_mul_f32_e32 v94, v99, v99
	v_fmac_f32_e32 v93, v95, v95
	v_fmac_f32_e32 v94, v98, v98
	v_add_f32_e32 v93, v93, v94
	v_add_f32_e32 v92, v92, v93
	v_lshlrev_b32_e32 v93, 16, v136
	v_fmac_f32_e32 v93, 0.5, v84
	v_and_b32_e32 v84, 0xffff0000, v136
	v_and_b32_e32 v94, 0xffff0000, v137
	v_cvt_pk_bf16_f32 v90, v95, v97
	v_fmac_f32_e32 v84, 0.5, v85
	v_lshlrev_b32_e32 v85, 16, v137
	v_fmac_f32_e32 v94, 0.5, v87
	v_lshlrev_b32_e32 v95, 16, v138
	v_and_b32_e32 v96, 0xffff0000, v138
	v_cvt_pk_bf16_f32 v91, v98, v99
	v_fmac_f32_e32 v85, 0.5, v86
	v_fmac_f32_e32 v95, 0.5, v80
	v_fmac_f32_e32 v96, 0.5, v81
	v_and_b32_e32 v98, 0xffff0000, v139
	v_mul_f32_e32 v80, v84, v84
	v_mul_f32_e32 v81, v94, v94
	v_lshlrev_b32_e32 v97, 16, v139
	v_fmac_f32_e32 v98, 0.5, v83
	v_fmac_f32_e32 v80, v93, v93
	v_fmac_f32_e32 v81, v85, v85
	v_fmac_f32_e32 v97, 0.5, v82
	v_add_f32_e32 v80, v80, v81
	v_mul_f32_e32 v81, v96, v96
	v_mul_f32_e32 v82, v98, v98
	v_fmac_f32_e32 v81, v95, v95
	v_fmac_f32_e32 v82, v97, v97
	v_add_f32_e32 v81, v81, v82
	v_add_f32_e32 v80, v80, v81
	v_add_f32_e32 v83, v92, v80
	ds_bpermute_b32 v92, v112, v83
	v_lshl_add_u64 v[80:81], s[0:1], 0, v[176:177]
	v_lshl_add_u64 v[86:87], v[164:165], 1, v[80:81]
	global_store_dwordx4 v[86:87], v[88:91], off
	v_cvt_pk_bf16_f32 v82, v93, v84
	s_waitcnt lgkmcnt(0)
	v_add_f32_e32 v80, v83, v92
	ds_bpermute_b32 v81, v113, v80
	v_cvt_pk_bf16_f32 v83, v85, v94
	v_cvt_pk_bf16_f32 v84, v95, v96
	v_cvt_pk_bf16_f32 v85, v97, v98
	global_store_dwordx4 v[86:87], v[82:85], off offset:256
	s_and_saveexec_b64 s[20:21], s[4:5]
	s_cbranch_execz .LBB0_1913
	s_waitcnt lgkmcnt(0)
	v_add_f32_e32 v82, v80, v81
	s_lshl_b32 s22, s30, 2
	v_lshlrev_b64 v[80:81], 7, v[174:175]
	s_ashr_i32 s23, s22, 31
	v_lshl_add_u64 v[80:81], s[8:9], 0, v[80:81]
	v_lshl_add_u64 v[80:81], s[22:23], 2, v[80:81]
	s_lshl_b32 s2, s41, 2
	v_lshl_add_u64 v[80:81], v[80:81], 0, s[2:3]
	global_store_dword v[80:81], v82, off
